# priority raised before the pre-MFMA barrier and dropped after the post-MFMA barrier (no setprio on the MFMA path), on top of v062
# speedup vs baseline: 1.0065x; 1.0023x over previous
; #define PG8_STAGE(bufoff, gbase, voff) do { _Pragma("unroll") for (int _i = 0; _i < 2; ++_i) \
;         __builtin_amdgcn_global_load_lds((const unsigned*)((const char*)(gbase) + (voff)[_i]), (PG8_LAS unsigned*)(lds + (bufoff) + ldsw + _i * 8192), 16, 0, 0); } while (0)
; #define PG8_LDA(dst, b, h) do { _Pragma("unroll") for (int m = 0; m < 4; ++m) _Pragma("unroll") for (int k = 0; k < 2; ++k) dst[m][k] = *(const PG8_LAS bf16x8*)(lds + PG8_SA(b, h) + aoff + m * 2048 + k * 1024); } while (0)
; #define PG8_LDB(dst, b, h) do { _Pragma("unroll") for (int n = 0; n < 2; ++n) _Pragma("unroll") for (int k = 0; k < 2; ++k) dst[n][k] = *(const PG8_LAS bf16x8*)(lds + PG8_SB(b, h) + boff + n * 2048 + k * 1024); } while (0)
; #define PG8_MMA(ai, bj, At, Bt) do { __builtin_amdgcn_s_setprio(1); _Pragma("unroll") for (int m = 0; m < 4; ++m) _Pragma("unroll") for (int n = 0; n < 2; ++n) _Pragma("unroll") for (int k = 0; k < 2; ++k) \
;         acc[ai][bj][m][n] = __builtin_amdgcn_mfma_f32_16x16x32_bf16(Bt[n][k], At[m][k], acc[ai][bj][m][n], 0, 0, 0); __builtin_amdgcn_s_setprio(0); } while (0)
; #define PG8_WAIT_V(n) asm volatile("s_waitcnt vmcnt(" #n ")" ::: "memory")
; #define PG8_WAIT_L(n) asm volatile("s_waitcnt lgkmcnt(" #n ")" ::: "memory")
; #define PG8_BAR __builtin_amdgcn_s_barrier()
; #define PG8_SCHED __builtin_amdgcn_sched_barrier(0)
; template <class Epi, class Sched, bool ALIGN_EPI = false, bool SP2 = false>
; __device__ __forceinline__ void gemm_phase(PG8_LAS unsigned char* lds, const Gemm g, const Sched& S, const Epi& E) {
;     ...
;             PG8_LDB(B0, 0, 0); PG8_LDB(B1, 0, 1); PG8_SCHED; PG8_LDA(At, 0, 0); PG8_STAGE(PG8_SA(1, 1), a1 + hstep, voffA);
;             PG8_WAIT_V(8); PG8_WAIT_L(0); PG8_BAR; PG8_MMA(0, 0, At, B0); PG8_MMA(0, 1, At, B1); PG8_BAR; PG8_SCHED;
;             PG8_LDA(At, 0, 1); PG8_STAGE(PG8_SB(0, 0), b2, voffB); PG8_STAGE(PG8_SB(0, 1), b2 + hstep, voffB); PG8_STAGE(PG8_SA(0, 0), a2, voffA);
;             PG8_WAIT_V(8); PG8_WAIT_L(0); PG8_BAR; PG8_MMA(1, 0, At, B0); PG8_MMA(1, 1, At, B1); PG8_BAR; PG8_SCHED;
.LBB0_180:
	s_add_u32 s36, s34, 0xfff00000
	s_addc_u32 s37, s35, -1
	s_mov_b32 m0, s45
	s_nop 0
	global_load_lds_dwordx4 v138, s[36:37]
	s_mov_b32 m0, s46
	s_nop 0
	global_load_lds_dwordx4 v142, s[36:37]
	s_add_u32 s36, s36, 0x80
	s_addc_u32 s37, s37, 0
	ds_read_b128 v[130:133], v170
	ds_read_b128 v[134:137], v170 offset:1024
	ds_read_b128 v[178:181], v170 offset:2048
	ds_read_b128 v[182:185], v170 offset:3072
	ds_read_b128 v[186:189], v171
	ds_read_b128 v[190:193], v171 offset:1024
	ds_read_b128 v[194:197], v171 offset:2048
	ds_read_b128 v[200:203], v171 offset:3072
	s_cmp_eq_u32 s56, 60
	s_cselect_b32 s39, s7, s37
	s_cselect_b32 s38, s25, s36
	s_cselect_b32 s37, s15, s55
	s_cselect_b32 s36, s31, s54
	s_add_i32 m0, s40, 0xc000
	ds_read_b128 v[204:207], v172
	ds_read_b128 v[208:211], v172 offset:1024
	ds_read_b128 v[212:215], v172 offset:2048
	ds_read_b128 v[216:219], v172 offset:3072
	ds_read_b128 v[220:223], v172 offset:4096
	ds_read_b128 v[224:227], v172 offset:5120
	ds_read_b128 v[228:231], v172 offset:6144
	ds_read_b128 v[232:235], v172 offset:7168
	global_load_lds_dwordx4 v148, s[34:35]
	s_add_i32 m0, s40, 0xe000
	s_nop 0
	global_load_lds_dwordx4 v150, s[34:35]
	s_waitcnt vmcnt(8)
	s_waitcnt lgkmcnt(0)
	s_setprio 1
	s_barrier
	v_mfma_f32_16x16x32_bf16 v[126:129], v[130:133], v[204:207], v[126:129]
	v_mfma_f32_16x16x32_bf16 v[122:125], v[178:181], v[204:207], v[122:125]
	v_mfma_f32_16x16x32_bf16 v[110:113], v[130:133], v[212:215], v[110:113]
	v_mfma_f32_16x16x32_bf16 v[106:109], v[178:181], v[212:215], v[106:109]
	v_mfma_f32_16x16x32_bf16 v[94:97], v[130:133], v[220:223], v[94:97]
	v_mfma_f32_16x16x32_bf16 v[90:93], v[178:181], v[220:223], v[90:93]
	v_mfma_f32_16x16x32_bf16 v[78:81], v[130:133], v[228:231], v[78:81]
	v_mfma_f32_16x16x32_bf16 v[74:77], v[178:181], v[228:231], v[74:77]
	v_mfma_f32_16x16x32_bf16 v[126:129], v[134:137], v[208:211], v[126:129]
	v_mfma_f32_16x16x32_bf16 v[122:125], v[182:185], v[208:211], v[122:125]
	v_mfma_f32_16x16x32_bf16 v[110:113], v[134:137], v[216:219], v[110:113]
	v_mfma_f32_16x16x32_bf16 v[106:109], v[182:185], v[216:219], v[106:109]
	v_mfma_f32_16x16x32_bf16 v[94:97], v[134:137], v[224:227], v[94:97]
	v_mfma_f32_16x16x32_bf16 v[90:93], v[182:185], v[224:227], v[90:93]
	v_mfma_f32_16x16x32_bf16 v[78:81], v[134:137], v[232:235], v[78:81]
	v_mfma_f32_16x16x32_bf16 v[74:77], v[182:185], v[232:235], v[74:77]
	v_mfma_f32_16x16x32_bf16 v[118:121], v[186:189], v[204:207], v[118:121]
	v_mfma_f32_16x16x32_bf16 v[114:117], v[194:197], v[204:207], v[114:117]
	v_mfma_f32_16x16x32_bf16 v[102:105], v[186:189], v[212:215], v[102:105]
	v_mfma_f32_16x16x32_bf16 v[98:101], v[194:197], v[212:215], v[98:101]
	v_mfma_f32_16x16x32_bf16 v[86:89], v[186:189], v[220:223], v[86:89]
	v_mfma_f32_16x16x32_bf16 v[82:85], v[194:197], v[220:223], v[82:85]
	v_mfma_f32_16x16x32_bf16 v[70:73], v[186:189], v[228:231], v[70:73]
	v_mfma_f32_16x16x32_bf16 v[66:69], v[194:197], v[228:231], v[66:69]
	v_mfma_f32_16x16x32_bf16 v[118:121], v[190:193], v[208:211], v[118:121]
	v_mfma_f32_16x16x32_bf16 v[114:117], v[200:203], v[208:211], v[114:117]
	v_mfma_f32_16x16x32_bf16 v[102:105], v[190:193], v[216:219], v[102:105]
	v_mfma_f32_16x16x32_bf16 v[98:101], v[200:203], v[216:219], v[98:101]
	v_mfma_f32_16x16x32_bf16 v[86:89], v[190:193], v[224:227], v[86:89]
	v_mfma_f32_16x16x32_bf16 v[82:85], v[200:203], v[224:227], v[82:85]
	v_mfma_f32_16x16x32_bf16 v[70:73], v[190:193], v[232:235], v[70:73]
	v_mfma_f32_16x16x32_bf16 v[66:69], v[200:203], v[232:235], v[66:69]
	s_barrier
	s_setprio 0
	s_add_i32 s57, s49, s33
	s_mov_b32 m0, s57
	ds_read_b128 v[204:207], v172 offset:16384
	ds_read_b128 v[208:211], v172 offset:17408
	ds_read_b128 v[212:215], v172 offset:18432
	ds_read_b128 v[216:219], v172 offset:19456
	ds_read_b128 v[220:223], v172 offset:20480
	ds_read_b128 v[224:227], v172 offset:21504
	ds_read_b128 v[228:231], v172 offset:22528
	ds_read_b128 v[232:235], v172 offset:23552
	global_load_lds_dwordx4 v140, s[36:37]
	s_add_i32 m0, s57, 0x2000
	s_add_u32 s58, s36, 0x100000
	s_addc_u32 s59, s37, 0
	s_add_i32 s57, s50, s33
	global_load_lds_dwordx4 v144, s[36:37]
	s_mov_b32 m0, s57
	s_nop 0
	global_load_lds_dwordx4 v140, s[58:59]
	s_add_i32 m0, s57, 0x2000
	s_nop 0
	global_load_lds_dwordx4 v144, s[58:59]
	s_waitcnt vmcnt(6)
	s_waitcnt lgkmcnt(0)
	s_setprio 1
	s_barrier
	v_mfma_f32_16x16x32_bf16 v[62:65], v[130:133], v[204:207], v[62:65]
	v_mfma_f32_16x16x32_bf16 v[58:61], v[178:181], v[204:207], v[58:61]
	v_mfma_f32_16x16x32_bf16 v[46:49], v[130:133], v[212:215], v[46:49]
	v_mfma_f32_16x16x32_bf16 v[42:45], v[178:181], v[212:215], v[42:45]
	v_mfma_f32_16x16x32_bf16 v[30:33], v[130:133], v[220:223], v[30:33]
	v_mfma_f32_16x16x32_bf16 v[26:29], v[178:181], v[220:223], v[26:29]
	v_mfma_f32_16x16x32_bf16 v[14:17], v[130:133], v[228:231], v[14:17]
	v_mfma_f32_16x16x32_bf16 v[10:13], v[178:181], v[228:231], v[10:13]
	v_mfma_f32_16x16x32_bf16 v[62:65], v[134:137], v[208:211], v[62:65]
	v_mfma_f32_16x16x32_bf16 v[58:61], v[182:185], v[208:211], v[58:61]
	v_mfma_f32_16x16x32_bf16 v[46:49], v[134:137], v[216:219], v[46:49]
	v_mfma_f32_16x16x32_bf16 v[42:45], v[182:185], v[216:219], v[42:45]
	v_mfma_f32_16x16x32_bf16 v[30:33], v[134:137], v[224:227], v[30:33]
	v_mfma_f32_16x16x32_bf16 v[26:29], v[182:185], v[224:227], v[26:29]
	v_mfma_f32_16x16x32_bf16 v[14:17], v[134:137], v[232:235], v[14:17]
	v_mfma_f32_16x16x32_bf16 v[10:13], v[182:185], v[232:235], v[10:13]
	v_mfma_f32_16x16x32_bf16 v[54:57], v[186:189], v[204:207], v[54:57]
	v_mfma_f32_16x16x32_bf16 v[50:53], v[194:197], v[204:207], v[50:53]
	v_mfma_f32_16x16x32_bf16 v[38:41], v[186:189], v[212:215], v[38:41]
	v_mfma_f32_16x16x32_bf16 v[34:37], v[194:197], v[212:215], v[34:37]
	v_mfma_f32_16x16x32_bf16 v[22:25], v[186:189], v[220:223], v[22:25]
	v_mfma_f32_16x16x32_bf16 v[18:21], v[194:197], v[220:223], v[18:21]
	v_mfma_f32_16x16x32_bf16 v[6:9], v[186:189], v[228:231], v[6:9]
	v_mfma_f32_16x16x32_bf16 v[2:5], v[194:197], v[228:231], v[2:5]
	v_mfma_f32_16x16x32_bf16 v[54:57], v[190:193], v[208:211], v[54:57]
	v_mfma_f32_16x16x32_bf16 v[50:53], v[200:203], v[208:211], v[50:53]
	v_mfma_f32_16x16x32_bf16 v[38:41], v[190:193], v[216:219], v[38:41]
	v_mfma_f32_16x16x32_bf16 v[34:37], v[200:203], v[216:219], v[34:37]
	v_mfma_f32_16x16x32_bf16 v[22:25], v[190:193], v[224:227], v[22:25]
	v_mfma_f32_16x16x32_bf16 v[18:21], v[200:203], v[224:227], v[18:21]
	v_mfma_f32_16x16x32_bf16 v[6:9], v[190:193], v[232:235], v[6:9]
	v_mfma_f32_16x16x32_bf16 v[2:5], v[200:203], v[232:235], v[2:5]
	s_barrier
; #define PG8_STAGE(bufoff, gbase, voff) do { _Pragma("unroll") for (int _i = 0; _i < 2; ++_i) \
;         __builtin_amdgcn_global_load_lds((const unsigned*)((const char*)(gbase) + (voff)[_i]), (PG8_LAS unsigned*)(lds + (bufoff) + ldsw + _i * 8192), 16, 0, 0); } while (0)
; #define PG8_LDA(dst, b, h) do { _Pragma("unroll") for (int m = 0; m < 4; ++m) _Pragma("unroll") for (int k = 0; k < 2; ++k) dst[m][k] = *(const PG8_LAS bf16x8*)(lds + PG8_SA(b, h) + aoff + m * 2048 + k * 1024); } while (0)
; #define PG8_LDB(dst, b, h) do { _Pragma("unroll") for (int n = 0; n < 2; ++n) _Pragma("unroll") for (int k = 0; k < 2; ++k) dst[n][k] = *(const PG8_LAS bf16x8*)(lds + PG8_SB(b, h) + boff + n * 2048 + k * 1024); } while (0)
; #define PG8_MMA(ai, bj, At, Bt) do { __builtin_amdgcn_s_setprio(1); _Pragma("unroll") for (int m = 0; m < 4; ++m) _Pragma("unroll") for (int n = 0; n < 2; ++n) _Pragma("unroll") for (int k = 0; k < 2; ++k) \
;         acc[ai][bj][m][n] = __builtin_amdgcn_mfma_f32_16x16x32_bf16(Bt[n][k], At[m][k], acc[ai][bj][m][n], 0, 0, 0); __builtin_amdgcn_s_setprio(0); } while (0)
; #define PG8_WAIT_V(n) asm volatile("s_waitcnt vmcnt(" #n ")" ::: "memory")
; #define PG8_WAIT_L(n) asm volatile("s_waitcnt lgkmcnt(" #n ")" ::: "memory")
; #define PG8_BAR __builtin_amdgcn_s_barrier()
; #define PG8_SCHED __builtin_amdgcn_sched_barrier(0)
; template <class Epi, class Sched, bool ALIGN_EPI = false, bool SP2 = false>
; __device__ __forceinline__ void gemm_phase(PG8_LAS unsigned char* lds, const Gemm g, const Sched& S, const Epi& E) {
;     ...
;             PG8_WAIT_V(8); PG8_WAIT_L(0); PG8_BAR; PG8_MMA(1, 0, At, B0); PG8_MMA(1, 1, At, B1); PG8_BAR; PG8_SCHED;
;             PG8_LDB(B0, 1, 0); PG8_LDB(B1, 1, 1); PG8_SCHED; PG8_LDA(At, 1, 0); PG8_STAGE(PG8_SA(0, 1), a2 + hstep, voffA);
;             PG8_WAIT_V(8); PG8_WAIT_L(0); PG8_BAR; PG8_MMA(0, 0, At, B0); PG8_MMA(0, 1, At, B1); PG8_BAR; PG8_SCHED;
;             PG8_LDA(At, 1, 1); PG8_STAGE(PG8_SB(1, 0), b3, voffB); PG8_STAGE(PG8_SB(1, 1), b3 + hstep, voffB); PG8_STAGE(PG8_SA(1, 0), a3, voffA);
;             PG8_WAIT_V(8); PG8_WAIT_L(0); PG8_BAR; PG8_MMA(1, 0, At, B0); PG8_MMA(1, 1, At, B1); PG8_BAR; PG8_SCHED;
;     ...
;         if constexpr (ALIGN_EPI) { if (wr == 0) PG8_BAR; }
	s_setprio 0
	s_mov_b32 m0, s40
	s_nop 0
	global_load_lds_dwordx4 v138, s[38:39]
	s_mov_b32 m0, s41
	s_nop 0
	global_load_lds_dwordx4 v142, s[38:39]
	s_add_i32 s57, 0, 0x18000
	v_add_u32_e32 v146, s57, v159
	s_add_i32 s58, 0, 0x1c000
	ds_read_b128 v[130:133], v146
	ds_read_b128 v[134:137], v146 offset:1024
	ds_read_b128 v[178:181], v146 offset:2048
	ds_read_b128 v[182:185], v146 offset:3072
	v_add_u32_e32 v146, s58, v159
	ds_read_b128 v[186:189], v146
	ds_read_b128 v[190:193], v146 offset:1024
	ds_read_b128 v[194:197], v146 offset:2048
	ds_read_b128 v[200:203], v146 offset:3072
	s_add_u32 s38, s38, 0x100000
	s_addc_u32 s39, s39, 0
	s_mov_b32 m0, s42
	ds_read_b128 v[204:207], v172 offset:32768
	ds_read_b128 v[208:211], v172 offset:33792
	ds_read_b128 v[212:215], v172 offset:34816
	ds_read_b128 v[216:219], v172 offset:35840
	ds_read_b128 v[220:223], v172 offset:36864
	ds_read_b128 v[224:227], v172 offset:37888
	ds_read_b128 v[228:231], v172 offset:38912
	ds_read_b128 v[232:235], v172 offset:39936
	global_load_lds_dwordx4 v138, s[38:39]
	s_mov_b32 m0, s43
	s_nop 0
	global_load_lds_dwordx4 v142, s[38:39]
	s_waitcnt vmcnt(8)
	s_waitcnt lgkmcnt(0)
	s_setprio 1
	s_barrier
	v_mfma_f32_16x16x32_bf16 v[126:129], v[130:133], v[204:207], v[126:129]
	v_mfma_f32_16x16x32_bf16 v[122:125], v[178:181], v[204:207], v[122:125]
	v_mfma_f32_16x16x32_bf16 v[110:113], v[130:133], v[212:215], v[110:113]
	v_mfma_f32_16x16x32_bf16 v[106:109], v[178:181], v[212:215], v[106:109]
	v_mfma_f32_16x16x32_bf16 v[94:97], v[130:133], v[220:223], v[94:97]
	v_mfma_f32_16x16x32_bf16 v[90:93], v[178:181], v[220:223], v[90:93]
	v_mfma_f32_16x16x32_bf16 v[78:81], v[130:133], v[228:231], v[78:81]
	v_mfma_f32_16x16x32_bf16 v[74:77], v[178:181], v[228:231], v[74:77]
	v_mfma_f32_16x16x32_bf16 v[126:129], v[134:137], v[208:211], v[126:129]
	v_mfma_f32_16x16x32_bf16 v[122:125], v[182:185], v[208:211], v[122:125]
	v_mfma_f32_16x16x32_bf16 v[110:113], v[134:137], v[216:219], v[110:113]
	v_mfma_f32_16x16x32_bf16 v[106:109], v[182:185], v[216:219], v[106:109]
	v_mfma_f32_16x16x32_bf16 v[94:97], v[134:137], v[224:227], v[94:97]
	v_mfma_f32_16x16x32_bf16 v[90:93], v[182:185], v[224:227], v[90:93]
	v_mfma_f32_16x16x32_bf16 v[78:81], v[134:137], v[232:235], v[78:81]
	v_mfma_f32_16x16x32_bf16 v[74:77], v[182:185], v[232:235], v[74:77]
	v_mfma_f32_16x16x32_bf16 v[118:121], v[186:189], v[204:207], v[118:121]
	v_mfma_f32_16x16x32_bf16 v[114:117], v[194:197], v[204:207], v[114:117]
	v_mfma_f32_16x16x32_bf16 v[102:105], v[186:189], v[212:215], v[102:105]
	v_mfma_f32_16x16x32_bf16 v[98:101], v[194:197], v[212:215], v[98:101]
	v_mfma_f32_16x16x32_bf16 v[86:89], v[186:189], v[220:223], v[86:89]
	v_mfma_f32_16x16x32_bf16 v[82:85], v[194:197], v[220:223], v[82:85]
	v_mfma_f32_16x16x32_bf16 v[70:73], v[186:189], v[228:231], v[70:73]
	v_mfma_f32_16x16x32_bf16 v[66:69], v[194:197], v[228:231], v[66:69]
	v_mfma_f32_16x16x32_bf16 v[118:121], v[190:193], v[208:211], v[118:121]
	v_mfma_f32_16x16x32_bf16 v[114:117], v[200:203], v[208:211], v[114:117]
	v_mfma_f32_16x16x32_bf16 v[102:105], v[190:193], v[216:219], v[102:105]
	v_mfma_f32_16x16x32_bf16 v[98:101], v[200:203], v[216:219], v[98:101]
	v_mfma_f32_16x16x32_bf16 v[86:89], v[190:193], v[224:227], v[86:89]
	v_mfma_f32_16x16x32_bf16 v[82:85], v[200:203], v[224:227], v[82:85]
	v_mfma_f32_16x16x32_bf16 v[70:73], v[190:193], v[232:235], v[70:73]
	v_mfma_f32_16x16x32_bf16 v[66:69], v[200:203], v[232:235], v[66:69]
	s_barrier
	s_setprio 0
	s_add_i32 s38, s57, s33
	s_add_u32 s36, s36, 0x80
	s_addc_u32 s37, s37, 0
	s_mov_b32 m0, s38
	ds_read_b128 v[204:207], v172 offset:49152
	ds_read_b128 v[208:211], v172 offset:50176
	ds_read_b128 v[212:215], v172 offset:51200
	ds_read_b128 v[216:219], v172 offset:52224
	ds_read_b128 v[220:223], v172 offset:53248
	ds_read_b128 v[224:227], v172 offset:54272
	ds_read_b128 v[228:231], v172 offset:55296
	ds_read_b128 v[232:235], v172 offset:56320
	global_load_lds_dwordx4 v140, s[36:37]
	s_add_i32 m0, s38, 0x2000
	s_add_i32 s38, s58, s33
	global_load_lds_dwordx4 v144, s[36:37]
	s_add_u32 s36, s36, 0x100000
	s_addc_u32 s37, s37, 0
	s_mov_b32 m0, s38
	s_nop 0
	global_load_lds_dwordx4 v140, s[36:37]
	s_add_i32 m0, s38, 0x2000
	s_nop 0
	global_load_lds_dwordx4 v144, s[36:37]
	s_waitcnt vmcnt(6)
	s_waitcnt lgkmcnt(0)
	s_setprio 1
	s_barrier
	v_mfma_f32_16x16x32_bf16 v[62:65], v[130:133], v[204:207], v[62:65]
	v_mfma_f32_16x16x32_bf16 v[58:61], v[178:181], v[204:207], v[58:61]
	v_mfma_f32_16x16x32_bf16 v[46:49], v[130:133], v[212:215], v[46:49]
	v_mfma_f32_16x16x32_bf16 v[42:45], v[178:181], v[212:215], v[42:45]
	v_mfma_f32_16x16x32_bf16 v[30:33], v[130:133], v[220:223], v[30:33]
	v_mfma_f32_16x16x32_bf16 v[26:29], v[178:181], v[220:223], v[26:29]
	v_mfma_f32_16x16x32_bf16 v[14:17], v[130:133], v[228:231], v[14:17]
	v_mfma_f32_16x16x32_bf16 v[10:13], v[178:181], v[228:231], v[10:13]
	v_mfma_f32_16x16x32_bf16 v[62:65], v[134:137], v[208:211], v[62:65]
	v_mfma_f32_16x16x32_bf16 v[58:61], v[182:185], v[208:211], v[58:61]
	v_mfma_f32_16x16x32_bf16 v[46:49], v[134:137], v[216:219], v[46:49]
	v_mfma_f32_16x16x32_bf16 v[42:45], v[182:185], v[216:219], v[42:45]
	v_mfma_f32_16x16x32_bf16 v[30:33], v[134:137], v[224:227], v[30:33]
	v_mfma_f32_16x16x32_bf16 v[26:29], v[182:185], v[224:227], v[26:29]
	v_mfma_f32_16x16x32_bf16 v[14:17], v[134:137], v[232:235], v[14:17]
	v_mfma_f32_16x16x32_bf16 v[10:13], v[182:185], v[232:235], v[10:13]
	v_mfma_f32_16x16x32_bf16 v[54:57], v[186:189], v[204:207], v[54:57]
	v_mfma_f32_16x16x32_bf16 v[50:53], v[194:197], v[204:207], v[50:53]
	v_mfma_f32_16x16x32_bf16 v[38:41], v[186:189], v[212:215], v[38:41]
	v_mfma_f32_16x16x32_bf16 v[34:37], v[194:197], v[212:215], v[34:37]
	v_mfma_f32_16x16x32_bf16 v[22:25], v[186:189], v[220:223], v[22:25]
	v_mfma_f32_16x16x32_bf16 v[18:21], v[194:197], v[220:223], v[18:21]
	v_mfma_f32_16x16x32_bf16 v[6:9], v[186:189], v[228:231], v[6:9]
	v_mfma_f32_16x16x32_bf16 v[2:5], v[194:197], v[228:231], v[2:5]
	v_mfma_f32_16x16x32_bf16 v[54:57], v[190:193], v[208:211], v[54:57]
	v_mfma_f32_16x16x32_bf16 v[50:53], v[200:203], v[208:211], v[50:53]
	v_mfma_f32_16x16x32_bf16 v[38:41], v[190:193], v[216:219], v[38:41]
	v_mfma_f32_16x16x32_bf16 v[34:37], v[200:203], v[216:219], v[34:37]
	v_mfma_f32_16x16x32_bf16 v[22:25], v[190:193], v[224:227], v[22:25]
	v_mfma_f32_16x16x32_bf16 v[18:21], v[200:203], v[224:227], v[18:21]
	v_mfma_f32_16x16x32_bf16 v[6:9], v[190:193], v[232:235], v[6:9]
	v_mfma_f32_16x16x32_bf16 v[2:5], v[200:203], v[232:235], v[2:5]
	s_barrier
	s_setprio 0
	s_add_i32 s56, s56, 2
	s_add_u32 s34, s34, 0x100
	s_addc_u32 s35, s35, 0
	s_add_u32 s54, s54, 0x100
	s_addc_u32 s55, s55, 0
	s_cmp_gt_u32 s56, 61
	s_cbranch_scc0 .LBB0_180
	s_and_b64 vcc, exec, s[12:13]
	s_cbranch_vccz .LBB0_183
	s_barrier

; #define PG8_STAGE(bufoff, gbase, voff) do { _Pragma("unroll") for (int _i = 0; _i < 2; ++_i) \
;         __builtin_amdgcn_global_load_lds((const unsigned*)((const char*)(gbase) + (voff)[_i]), (PG8_LAS unsigned*)(lds + (bufoff) + ldsw + _i * 8192), 16, 0, 0); } while (0)
; #define PG8_LDA(dst, b, h) do { _Pragma("unroll") for (int m = 0; m < 4; ++m) _Pragma("unroll") for (int k = 0; k < 2; ++k) dst[m][k] = *(const PG8_LAS bf16x8*)(lds + PG8_SA(b, h) + aoff + m * 2048 + k * 1024); } while (0)
; #define PG8_LDB(dst, b, h) do { _Pragma("unroll") for (int n = 0; n < 2; ++n) _Pragma("unroll") for (int k = 0; k < 2; ++k) dst[n][k] = *(const PG8_LAS bf16x8*)(lds + PG8_SB(b, h) + boff + n * 2048 + k * 1024); } while (0)
; #define PG8_MMA(ai, bj, At, Bt) do { __builtin_amdgcn_s_setprio(1); _Pragma("unroll") for (int m = 0; m < 4; ++m) _Pragma("unroll") for (int n = 0; n < 2; ++n) _Pragma("unroll") for (int k = 0; k < 2; ++k) \
;         acc[ai][bj][m][n] = __builtin_amdgcn_mfma_f32_16x16x32_bf16(Bt[n][k], At[m][k], acc[ai][bj][m][n], 0, 0, 0); __builtin_amdgcn_s_setprio(0); } while (0)
; #define PG8_WAIT_V(n) asm volatile("s_waitcnt vmcnt(" #n ")" ::: "memory")
; #define PG8_BAR __builtin_amdgcn_s_barrier()
; template <class Epi, class Sched, bool ALIGN_EPI = false, bool SP2 = false>
; __device__ __forceinline__ void gemm_phase(PG8_LAS unsigned char* lds, const Gemm g, const Sched& S, const Epi& E) {
;     ...
;         for (int t = 0; t < nt; t += 2) {
;             const bool last = (t == nt - 2);
;             const char* a1 = cA + (size_t)(t + 1) * kstep;
;             const char* a2 = last ? nA : cA + (size_t)(t + 2) * kstep; const char* b2 = last ? nB : cB + (size_t)(t + 2) * kstep;
;             const char* a3 = a2 + kstep; const char* b3 = b2 + kstep;
;             if (last && has_next) S.a_ready(nxt);
;             if constexpr (SP2) {
;             PG8_LDB(B0, 0, 0); PG8_LDB(B1, 0, 1); PG8_SCHED; PG8_LDA(At, 0, 0); PG8_STAGE(PG8_SA(1, 1), a1 + hstep, voffA);
;             PG8_WAIT_V(8); PG8_WAIT_L(0); PG8_BAR; PG8_MMA(0, 0, At, B0); PG8_MMA(0, 1, At, B1); PG8_BAR; PG8_SCHED;
;             PG8_LDA(At, 0, 1); PG8_STAGE(PG8_SB(0, 0), b2, voffB); PG8_STAGE(PG8_SB(0, 1), b2 + hstep, voffB); PG8_STAGE(PG8_SA(0, 0), a2, voffA);
;             PG8_WAIT_V(8); PG8_WAIT_L(0); PG8_BAR; PG8_MMA(1, 0, At, B0); PG8_MMA(1, 1, At, B1); PG8_BAR; PG8_SCHED;
.LBB0_857:
	s_add_u32 s34, s30, 0xfff80000
	s_addc_u32 s35, s31, -1
	s_mov_b32 m0, s43
	s_nop 0
	global_load_lds_dwordx4 v150, s[34:35]
	s_mov_b32 m0, s44
	s_nop 0
	global_load_lds_dwordx4 v154, s[34:35]
	s_add_u32 s34, s34, 0x80
	s_addc_u32 s35, s35, 0
	ds_read_b128 v[130:133], v180
	ds_read_b128 v[134:137], v180 offset:1024
	ds_read_b128 v[138:141], v180 offset:2048
	ds_read_b128 v[142:145], v180 offset:3072
	ds_read_b128 v[146:149], v181
	ds_read_b128 v[166:169], v181 offset:1024
	ds_read_b128 v[170:173], v181 offset:2048
	ds_read_b128 v[174:177], v181 offset:3072
	s_cmp_eq_u32 s56, 28
	s_cselect_b32 s37, s15, s35
	s_cselect_b32 s36, s50, s34
	s_cselect_b32 s35, s13, s53
	s_cselect_b32 s34, s51, s52
	s_add_i32 m0, s29, 0xc000
	ds_read_b128 v[184:187], v182
	ds_read_b128 v[188:191], v182 offset:1024
	ds_read_b128 v[192:195], v182 offset:2048
	ds_read_b128 v[200:203], v182 offset:3072
	ds_read_b128 v[204:207], v182 offset:4096
	ds_read_b128 v[208:211], v182 offset:5120
	ds_read_b128 v[212:215], v182 offset:6144
	ds_read_b128 v[216:219], v182 offset:7168
	global_load_lds_dwordx4 v158, s[30:31]
	s_add_i32 m0, s29, 0xe000
	s_nop 0
	global_load_lds_dwordx4 v160, s[30:31]
	s_waitcnt vmcnt(8)
	s_waitcnt lgkmcnt(0)
	s_setprio 1
	s_barrier
	v_mfma_f32_16x16x32_bf16 v[126:129], v[130:133], v[184:187], v[126:129]
	v_mfma_f32_16x16x32_bf16 v[122:125], v[138:141], v[184:187], v[122:125]
	v_mfma_f32_16x16x32_bf16 v[110:113], v[130:133], v[192:195], v[110:113]
	v_mfma_f32_16x16x32_bf16 v[106:109], v[138:141], v[192:195], v[106:109]
	v_mfma_f32_16x16x32_bf16 v[94:97], v[130:133], v[204:207], v[94:97]
	v_mfma_f32_16x16x32_bf16 v[90:93], v[138:141], v[204:207], v[90:93]
	v_mfma_f32_16x16x32_bf16 v[78:81], v[130:133], v[212:215], v[78:81]
	v_mfma_f32_16x16x32_bf16 v[74:77], v[138:141], v[212:215], v[74:77]
	v_mfma_f32_16x16x32_bf16 v[126:129], v[134:137], v[188:191], v[126:129]
	v_mfma_f32_16x16x32_bf16 v[122:125], v[142:145], v[188:191], v[122:125]
	v_mfma_f32_16x16x32_bf16 v[110:113], v[134:137], v[200:203], v[110:113]
	v_mfma_f32_16x16x32_bf16 v[106:109], v[142:145], v[200:203], v[106:109]
	v_mfma_f32_16x16x32_bf16 v[94:97], v[134:137], v[208:211], v[94:97]
	v_mfma_f32_16x16x32_bf16 v[90:93], v[142:145], v[208:211], v[90:93]
	v_mfma_f32_16x16x32_bf16 v[78:81], v[134:137], v[216:219], v[78:81]
	v_mfma_f32_16x16x32_bf16 v[74:77], v[142:145], v[216:219], v[74:77]
	v_mfma_f32_16x16x32_bf16 v[118:121], v[146:149], v[184:187], v[118:121]
	v_mfma_f32_16x16x32_bf16 v[114:117], v[170:173], v[184:187], v[114:117]
	v_mfma_f32_16x16x32_bf16 v[102:105], v[146:149], v[192:195], v[102:105]
	v_mfma_f32_16x16x32_bf16 v[98:101], v[170:173], v[192:195], v[98:101]
	v_mfma_f32_16x16x32_bf16 v[86:89], v[146:149], v[204:207], v[86:89]
	v_mfma_f32_16x16x32_bf16 v[82:85], v[170:173], v[204:207], v[82:85]
	v_mfma_f32_16x16x32_bf16 v[70:73], v[146:149], v[212:215], v[70:73]
	v_mfma_f32_16x16x32_bf16 v[66:69], v[170:173], v[212:215], v[66:69]
	v_mfma_f32_16x16x32_bf16 v[118:121], v[166:169], v[188:191], v[118:121]
	v_mfma_f32_16x16x32_bf16 v[114:117], v[174:177], v[188:191], v[114:117]
	v_mfma_f32_16x16x32_bf16 v[102:105], v[166:169], v[200:203], v[102:105]
	v_mfma_f32_16x16x32_bf16 v[98:101], v[174:177], v[200:203], v[98:101]
	v_mfma_f32_16x16x32_bf16 v[86:89], v[166:169], v[208:211], v[86:89]
	v_mfma_f32_16x16x32_bf16 v[82:85], v[174:177], v[208:211], v[82:85]
	v_mfma_f32_16x16x32_bf16 v[70:73], v[166:169], v[216:219], v[70:73]
	v_mfma_f32_16x16x32_bf16 v[66:69], v[174:177], v[216:219], v[66:69]
	s_barrier
	s_setprio 0
	s_add_i32 s57, s46, s38
	s_mov_b32 m0, s57
	ds_read_b128 v[184:187], v182 offset:16384
	ds_read_b128 v[188:191], v182 offset:17408
	ds_read_b128 v[192:195], v182 offset:18432
	ds_read_b128 v[200:203], v182 offset:19456
	ds_read_b128 v[204:207], v182 offset:20480
	ds_read_b128 v[208:211], v182 offset:21504
	ds_read_b128 v[212:215], v182 offset:22528
	ds_read_b128 v[216:219], v182 offset:23552
	global_load_lds_dwordx4 v152, s[34:35]
	s_add_i32 m0, s57, 0x2000
	s_add_u32 s58, s34, 0x80000
	s_addc_u32 s59, s35, 0
	s_add_i32 s57, s47, s38
	global_load_lds_dwordx4 v156, s[34:35]
	s_mov_b32 m0, s57
	s_nop 0
	global_load_lds_dwordx4 v152, s[58:59]
	s_add_i32 m0, s57, 0x2000
	s_nop 0
	global_load_lds_dwordx4 v156, s[58:59]
	s_waitcnt vmcnt(6)
	s_waitcnt lgkmcnt(0)
	s_setprio 1
	s_barrier
	v_mfma_f32_16x16x32_bf16 v[62:65], v[130:133], v[184:187], v[62:65]
	v_mfma_f32_16x16x32_bf16 v[58:61], v[138:141], v[184:187], v[58:61]
	v_mfma_f32_16x16x32_bf16 v[46:49], v[130:133], v[192:195], v[46:49]
	v_mfma_f32_16x16x32_bf16 v[42:45], v[138:141], v[192:195], v[42:45]
	v_mfma_f32_16x16x32_bf16 v[30:33], v[130:133], v[204:207], v[30:33]
	v_mfma_f32_16x16x32_bf16 v[26:29], v[138:141], v[204:207], v[26:29]
	v_mfma_f32_16x16x32_bf16 v[14:17], v[130:133], v[212:215], v[14:17]
	v_mfma_f32_16x16x32_bf16 v[10:13], v[138:141], v[212:215], v[10:13]
	v_mfma_f32_16x16x32_bf16 v[62:65], v[134:137], v[188:191], v[62:65]
	v_mfma_f32_16x16x32_bf16 v[58:61], v[142:145], v[188:191], v[58:61]
	v_mfma_f32_16x16x32_bf16 v[46:49], v[134:137], v[200:203], v[46:49]
	v_mfma_f32_16x16x32_bf16 v[42:45], v[142:145], v[200:203], v[42:45]
	v_mfma_f32_16x16x32_bf16 v[30:33], v[134:137], v[208:211], v[30:33]
	v_mfma_f32_16x16x32_bf16 v[26:29], v[142:145], v[208:211], v[26:29]
	v_mfma_f32_16x16x32_bf16 v[14:17], v[134:137], v[216:219], v[14:17]
	v_mfma_f32_16x16x32_bf16 v[10:13], v[142:145], v[216:219], v[10:13]
	v_mfma_f32_16x16x32_bf16 v[54:57], v[146:149], v[184:187], v[54:57]
	v_mfma_f32_16x16x32_bf16 v[50:53], v[170:173], v[184:187], v[50:53]
	v_mfma_f32_16x16x32_bf16 v[38:41], v[146:149], v[192:195], v[38:41]
	v_mfma_f32_16x16x32_bf16 v[34:37], v[170:173], v[192:195], v[34:37]
	v_mfma_f32_16x16x32_bf16 v[22:25], v[146:149], v[204:207], v[22:25]
	v_mfma_f32_16x16x32_bf16 v[18:21], v[170:173], v[204:207], v[18:21]
	v_mfma_f32_16x16x32_bf16 v[6:9], v[146:149], v[212:215], v[6:9]
	v_mfma_f32_16x16x32_bf16 v[2:5], v[170:173], v[212:215], v[2:5]
	v_mfma_f32_16x16x32_bf16 v[54:57], v[166:169], v[188:191], v[54:57]
	v_mfma_f32_16x16x32_bf16 v[50:53], v[174:177], v[188:191], v[50:53]
	v_mfma_f32_16x16x32_bf16 v[38:41], v[166:169], v[200:203], v[38:41]
	v_mfma_f32_16x16x32_bf16 v[34:37], v[174:177], v[200:203], v[34:37]
	v_mfma_f32_16x16x32_bf16 v[22:25], v[166:169], v[208:211], v[22:25]
	v_mfma_f32_16x16x32_bf16 v[18:21], v[174:177], v[208:211], v[18:21]
	v_mfma_f32_16x16x32_bf16 v[6:9], v[166:169], v[216:219], v[6:9]
	v_mfma_f32_16x16x32_bf16 v[2:5], v[174:177], v[216:219], v[2:5]
	s_barrier
; #define PG8_STAGE(bufoff, gbase, voff) do { _Pragma("unroll") for (int _i = 0; _i < 2; ++_i) \
;         __builtin_amdgcn_global_load_lds((const unsigned*)((const char*)(gbase) + (voff)[_i]), (PG8_LAS unsigned*)(lds + (bufoff) + ldsw + _i * 8192), 16, 0, 0); } while (0)
; #define PG8_LDA(dst, b, h) do { _Pragma("unroll") for (int m = 0; m < 4; ++m) _Pragma("unroll") for (int k = 0; k < 2; ++k) dst[m][k] = *(const PG8_LAS bf16x8*)(lds + PG8_SA(b, h) + aoff + m * 2048 + k * 1024); } while (0)
; #define PG8_LDB(dst, b, h) do { _Pragma("unroll") for (int n = 0; n < 2; ++n) _Pragma("unroll") for (int k = 0; k < 2; ++k) dst[n][k] = *(const PG8_LAS bf16x8*)(lds + PG8_SB(b, h) + boff + n * 2048 + k * 1024); } while (0)
; #define PG8_MMA(ai, bj, At, Bt) do { __builtin_amdgcn_s_setprio(1); _Pragma("unroll") for (int m = 0; m < 4; ++m) _Pragma("unroll") for (int n = 0; n < 2; ++n) _Pragma("unroll") for (int k = 0; k < 2; ++k) \
;         acc[ai][bj][m][n] = __builtin_amdgcn_mfma_f32_16x16x32_bf16(Bt[n][k], At[m][k], acc[ai][bj][m][n], 0, 0, 0); __builtin_amdgcn_s_setprio(0); } while (0)
; #define PG8_WAIT_V(n) asm volatile("s_waitcnt vmcnt(" #n ")" ::: "memory")
; #define PG8_WAIT_L(n) asm volatile("s_waitcnt lgkmcnt(" #n ")" ::: "memory")
; #define PG8_BAR __builtin_amdgcn_s_barrier()
; #define PG8_SCHED __builtin_amdgcn_sched_barrier(0)
; template <class Epi, class Sched, bool ALIGN_EPI = false, bool SP2 = false>
; __device__ __forceinline__ void gemm_phase(PG8_LAS unsigned char* lds, const Gemm g, const Sched& S, const Epi& E) {
;     ...
;             PG8_LDB(B0, 1, 0); PG8_LDB(B1, 1, 1); PG8_SCHED; PG8_LDA(At, 1, 0); PG8_STAGE(PG8_SA(0, 1), a2 + hstep, voffA);
;             PG8_WAIT_V(8); PG8_WAIT_L(0); PG8_BAR; PG8_MMA(0, 0, At, B0); PG8_MMA(0, 1, At, B1); PG8_BAR; PG8_SCHED;
;             PG8_LDA(At, 1, 1); PG8_STAGE(PG8_SB(1, 0), b3, voffB); PG8_STAGE(PG8_SB(1, 1), b3 + hstep, voffB); PG8_STAGE(PG8_SA(1, 0), a3, voffA);
;             PG8_WAIT_V(8); PG8_WAIT_L(0); PG8_BAR; PG8_MMA(1, 0, At, B0); PG8_MMA(1, 1, At, B1); PG8_BAR; PG8_SCHED;
;     ...
;         if constexpr (ALIGN_EPI) { if (wr == 0) PG8_BAR; }
	s_setprio 0
	s_mov_b32 m0, s29
	s_nop 0
	global_load_lds_dwordx4 v150, s[36:37]
	s_mov_b32 m0, s39
	s_nop 0
	global_load_lds_dwordx4 v154, s[36:37]
	s_add_i32 s57, 0, 0x18000
	s_add_i32 s58, 0, 0x1c000
	v_add_u32_e32 v142, s57, v178
	v_add_u32_e32 v174, s58, v178
	ds_read_b128 v[130:133], v142
	ds_read_b128 v[134:137], v142 offset:1024
	ds_read_b128 v[138:141], v142 offset:2048
	ds_read_b128 v[142:145], v142 offset:3072
	ds_read_b128 v[146:149], v174
	ds_read_b128 v[166:169], v174 offset:1024
	ds_read_b128 v[170:173], v174 offset:2048
	ds_read_b128 v[174:177], v174 offset:3072
	s_add_u32 s36, s36, 0x80000
	s_addc_u32 s37, s37, 0
	s_mov_b32 m0, s40
	ds_read_b128 v[184:187], v182 offset:32768
	ds_read_b128 v[188:191], v182 offset:33792
	ds_read_b128 v[192:195], v182 offset:34816
	ds_read_b128 v[200:203], v182 offset:35840
	ds_read_b128 v[204:207], v182 offset:36864
	ds_read_b128 v[208:211], v182 offset:37888
	ds_read_b128 v[212:215], v182 offset:38912
	ds_read_b128 v[216:219], v182 offset:39936
	global_load_lds_dwordx4 v150, s[36:37]
	s_mov_b32 m0, s41
	s_nop 0
	global_load_lds_dwordx4 v154, s[36:37]
	s_waitcnt vmcnt(8)
	s_waitcnt lgkmcnt(0)
	s_setprio 1
	s_barrier
	v_mfma_f32_16x16x32_bf16 v[126:129], v[130:133], v[184:187], v[126:129]
	v_mfma_f32_16x16x32_bf16 v[122:125], v[138:141], v[184:187], v[122:125]
	v_mfma_f32_16x16x32_bf16 v[110:113], v[130:133], v[192:195], v[110:113]
	v_mfma_f32_16x16x32_bf16 v[106:109], v[138:141], v[192:195], v[106:109]
	v_mfma_f32_16x16x32_bf16 v[94:97], v[130:133], v[204:207], v[94:97]
	v_mfma_f32_16x16x32_bf16 v[90:93], v[138:141], v[204:207], v[90:93]
	v_mfma_f32_16x16x32_bf16 v[78:81], v[130:133], v[212:215], v[78:81]
	v_mfma_f32_16x16x32_bf16 v[74:77], v[138:141], v[212:215], v[74:77]
	v_mfma_f32_16x16x32_bf16 v[126:129], v[134:137], v[188:191], v[126:129]
	v_mfma_f32_16x16x32_bf16 v[122:125], v[142:145], v[188:191], v[122:125]
	v_mfma_f32_16x16x32_bf16 v[110:113], v[134:137], v[200:203], v[110:113]
	v_mfma_f32_16x16x32_bf16 v[106:109], v[142:145], v[200:203], v[106:109]
	v_mfma_f32_16x16x32_bf16 v[94:97], v[134:137], v[208:211], v[94:97]
	v_mfma_f32_16x16x32_bf16 v[90:93], v[142:145], v[208:211], v[90:93]
	v_mfma_f32_16x16x32_bf16 v[78:81], v[134:137], v[216:219], v[78:81]
	v_mfma_f32_16x16x32_bf16 v[74:77], v[142:145], v[216:219], v[74:77]
	v_mfma_f32_16x16x32_bf16 v[118:121], v[146:149], v[184:187], v[118:121]
	v_mfma_f32_16x16x32_bf16 v[114:117], v[170:173], v[184:187], v[114:117]
	v_mfma_f32_16x16x32_bf16 v[102:105], v[146:149], v[192:195], v[102:105]
	v_mfma_f32_16x16x32_bf16 v[98:101], v[170:173], v[192:195], v[98:101]
	v_mfma_f32_16x16x32_bf16 v[86:89], v[146:149], v[204:207], v[86:89]
	v_mfma_f32_16x16x32_bf16 v[82:85], v[170:173], v[204:207], v[82:85]
	v_mfma_f32_16x16x32_bf16 v[70:73], v[146:149], v[212:215], v[70:73]
	v_mfma_f32_16x16x32_bf16 v[66:69], v[170:173], v[212:215], v[66:69]
	v_mfma_f32_16x16x32_bf16 v[118:121], v[166:169], v[188:191], v[118:121]
	v_mfma_f32_16x16x32_bf16 v[114:117], v[174:177], v[188:191], v[114:117]
	v_mfma_f32_16x16x32_bf16 v[102:105], v[166:169], v[200:203], v[102:105]
	v_mfma_f32_16x16x32_bf16 v[98:101], v[174:177], v[200:203], v[98:101]
	v_mfma_f32_16x16x32_bf16 v[86:89], v[166:169], v[208:211], v[86:89]
	v_mfma_f32_16x16x32_bf16 v[82:85], v[174:177], v[208:211], v[82:85]
	v_mfma_f32_16x16x32_bf16 v[70:73], v[166:169], v[216:219], v[70:73]
	v_mfma_f32_16x16x32_bf16 v[66:69], v[174:177], v[216:219], v[66:69]
	s_barrier
	s_setprio 0
	s_add_i32 s36, s57, s38
	s_add_u32 s34, s34, 0x80
	s_addc_u32 s35, s35, 0
	s_mov_b32 m0, s36
	ds_read_b128 v[184:187], v182 offset:49152
	ds_read_b128 v[188:191], v182 offset:50176
	ds_read_b128 v[192:195], v182 offset:51200
	ds_read_b128 v[200:203], v182 offset:52224
	ds_read_b128 v[204:207], v182 offset:53248
	ds_read_b128 v[208:211], v182 offset:54272
	ds_read_b128 v[212:215], v182 offset:55296
	ds_read_b128 v[216:219], v182 offset:56320
	global_load_lds_dwordx4 v152, s[34:35]
	s_add_i32 m0, s36, 0x2000
	s_add_i32 s36, s58, s38
	global_load_lds_dwordx4 v156, s[34:35]
	s_add_u32 s34, s34, 0x80000
	s_addc_u32 s35, s35, 0
	s_mov_b32 m0, s36
	s_nop 0
	global_load_lds_dwordx4 v152, s[34:35]
	s_add_i32 m0, s36, 0x2000
	s_nop 0
	global_load_lds_dwordx4 v156, s[34:35]
	s_waitcnt vmcnt(6)
	s_waitcnt lgkmcnt(0)
	s_setprio 1
	s_barrier
	v_mfma_f32_16x16x32_bf16 v[62:65], v[130:133], v[184:187], v[62:65]
	v_mfma_f32_16x16x32_bf16 v[58:61], v[138:141], v[184:187], v[58:61]
	v_mfma_f32_16x16x32_bf16 v[46:49], v[130:133], v[192:195], v[46:49]
	v_mfma_f32_16x16x32_bf16 v[42:45], v[138:141], v[192:195], v[42:45]
	v_mfma_f32_16x16x32_bf16 v[30:33], v[130:133], v[204:207], v[30:33]
	v_mfma_f32_16x16x32_bf16 v[26:29], v[138:141], v[204:207], v[26:29]
	v_mfma_f32_16x16x32_bf16 v[14:17], v[130:133], v[212:215], v[14:17]
	v_mfma_f32_16x16x32_bf16 v[10:13], v[138:141], v[212:215], v[10:13]
	v_mfma_f32_16x16x32_bf16 v[62:65], v[134:137], v[188:191], v[62:65]
	v_mfma_f32_16x16x32_bf16 v[58:61], v[142:145], v[188:191], v[58:61]
	v_mfma_f32_16x16x32_bf16 v[46:49], v[134:137], v[200:203], v[46:49]
	v_mfma_f32_16x16x32_bf16 v[42:45], v[142:145], v[200:203], v[42:45]
	v_mfma_f32_16x16x32_bf16 v[30:33], v[134:137], v[208:211], v[30:33]
	v_mfma_f32_16x16x32_bf16 v[26:29], v[142:145], v[208:211], v[26:29]
	v_mfma_f32_16x16x32_bf16 v[14:17], v[134:137], v[216:219], v[14:17]
	v_mfma_f32_16x16x32_bf16 v[10:13], v[142:145], v[216:219], v[10:13]
	v_mfma_f32_16x16x32_bf16 v[54:57], v[146:149], v[184:187], v[54:57]
	v_mfma_f32_16x16x32_bf16 v[50:53], v[170:173], v[184:187], v[50:53]
	v_mfma_f32_16x16x32_bf16 v[38:41], v[146:149], v[192:195], v[38:41]
	v_mfma_f32_16x16x32_bf16 v[34:37], v[170:173], v[192:195], v[34:37]
	v_mfma_f32_16x16x32_bf16 v[22:25], v[146:149], v[204:207], v[22:25]
	v_mfma_f32_16x16x32_bf16 v[18:21], v[170:173], v[204:207], v[18:21]
	v_mfma_f32_16x16x32_bf16 v[6:9], v[146:149], v[212:215], v[6:9]
	v_mfma_f32_16x16x32_bf16 v[2:5], v[170:173], v[212:215], v[2:5]
	v_mfma_f32_16x16x32_bf16 v[54:57], v[166:169], v[188:191], v[54:57]
	v_mfma_f32_16x16x32_bf16 v[50:53], v[174:177], v[188:191], v[50:53]
	v_mfma_f32_16x16x32_bf16 v[38:41], v[166:169], v[200:203], v[38:41]
	v_mfma_f32_16x16x32_bf16 v[34:37], v[174:177], v[200:203], v[34:37]
	v_mfma_f32_16x16x32_bf16 v[22:25], v[166:169], v[208:211], v[22:25]
	v_mfma_f32_16x16x32_bf16 v[18:21], v[174:177], v[208:211], v[18:21]
	v_mfma_f32_16x16x32_bf16 v[6:9], v[166:169], v[216:219], v[6:9]
	v_mfma_f32_16x16x32_bf16 v[2:5], v[174:177], v[216:219], v[2:5]
	s_barrier
	s_setprio 0
	s_add_i32 s56, s56, 2
	s_add_u32 s30, s30, 0x100
	s_addc_u32 s31, s31, 0
	s_add_u32 s52, s52, 0x100
	s_addc_u32 s53, s53, 0
	s_cmp_gt_u32 s56, 29
	s_cbranch_scc0 .LBB0_857
	s_and_b64 vcc, exec, s[10:11]
	s_cbranch_vccz .LBB0_860
	s_barrier

; #define PG8_STAGE(bufoff, gbase, voff) do { _Pragma("unroll") for (int _i = 0; _i < 2; ++_i) \
;         __builtin_amdgcn_global_load_lds((const unsigned*)((const char*)(gbase) + (voff)[_i]), (PG8_LAS unsigned*)(lds + (bufoff) + ldsw + _i * 8192), 16, 0, 0); } while (0)
; #define PG8_LDA(dst, b, h) do { _Pragma("unroll") for (int m = 0; m < 4; ++m) _Pragma("unroll") for (int k = 0; k < 2; ++k) dst[m][k] = *(const PG8_LAS bf16x8*)(lds + PG8_SA(b, h) + aoff + m * 2048 + k * 1024); } while (0)
; #define PG8_LDB(dst, b, h) do { _Pragma("unroll") for (int n = 0; n < 2; ++n) _Pragma("unroll") for (int k = 0; k < 2; ++k) dst[n][k] = *(const PG8_LAS bf16x8*)(lds + PG8_SB(b, h) + boff + n * 2048 + k * 1024); } while (0)
; #define PG8_MMA(ai, bj, At, Bt) do { __builtin_amdgcn_s_setprio(1); _Pragma("unroll") for (int m = 0; m < 4; ++m) _Pragma("unroll") for (int n = 0; n < 2; ++n) _Pragma("unroll") for (int k = 0; k < 2; ++k) \
;         acc[ai][bj][m][n] = __builtin_amdgcn_mfma_f32_16x16x32_bf16(Bt[n][k], At[m][k], acc[ai][bj][m][n], 0, 0, 0); __builtin_amdgcn_s_setprio(0); } while (0)
; #define PG8_WAIT_V(n) asm volatile("s_waitcnt vmcnt(" #n ")" ::: "memory")
; #define PG8_BAR __builtin_amdgcn_s_barrier()
; template <class Epi, class Sched, bool ALIGN_EPI = false, bool SP2 = false>
; __device__ __forceinline__ void gemm_phase(PG8_LAS unsigned char* lds, const Gemm g, const Sched& S, const Epi& E) {
;     ...
;         for (int t = 0; t < nt; t += 2) {
;             const bool last = (t == nt - 2);
;             const char* a1 = cA + (size_t)(t + 1) * kstep;
;             const char* a2 = last ? nA : cA + (size_t)(t + 2) * kstep; const char* b2 = last ? nB : cB + (size_t)(t + 2) * kstep;
;             const char* a3 = a2 + kstep; const char* b3 = b2 + kstep;
;             if (last && has_next) S.a_ready(nxt);
;             if constexpr (SP2) {
;             PG8_LDB(B0, 0, 0); PG8_LDB(B1, 0, 1); PG8_SCHED; PG8_LDA(At, 0, 0); PG8_STAGE(PG8_SA(1, 1), a1 + hstep, voffA);
;             PG8_WAIT_V(8); PG8_WAIT_L(0); PG8_BAR; PG8_MMA(0, 0, At, B0); PG8_MMA(0, 1, At, B1); PG8_BAR; PG8_SCHED;
;             PG8_LDA(At, 0, 1); PG8_STAGE(PG8_SB(0, 0), b2, voffB); PG8_STAGE(PG8_SB(0, 1), b2 + hstep, voffB); PG8_STAGE(PG8_SA(0, 0), a2, voffA);
;             PG8_WAIT_V(8); PG8_WAIT_L(0); PG8_BAR; PG8_MMA(1, 0, At, B0); PG8_MMA(1, 1, At, B1); PG8_BAR; PG8_SCHED;
.LBB0_884:
	s_add_u32 s34, s30, 0xfff80000
	s_addc_u32 s35, s31, -1
	s_mov_b32 m0, s43
	s_nop 0
	global_load_lds_dwordx4 v178, s[34:35]
	s_mov_b32 m0, s44
	s_nop 0
	global_load_lds_dwordx4 v182, s[34:35]
	s_add_u32 s34, s34, 0x80
	s_addc_u32 s35, s35, 0
	ds_read_b128 v[130:133], v211
	ds_read_b128 v[134:137], v211 offset:1024
	ds_read_b128 v[138:141], v211 offset:2048
	ds_read_b128 v[142:145], v211 offset:3072
	ds_read_b128 v[146:149], v212
	ds_read_b128 v[150:153], v212 offset:1024
	ds_read_b128 v[154:157], v212 offset:2048
	ds_read_b128 v[158:161], v212 offset:3072
	s_cmp_eq_u32 s56, 28
	s_cselect_b32 s37, s15, s35
	s_cselect_b32 s36, s50, s34
	s_cselect_b32 s35, s13, s53
	s_cselect_b32 s34, s51, s52
	s_add_i32 m0, s29, 0xc000
	ds_read_b128 v[162:165], v213
	ds_read_b128 v[166:169], v213 offset:1024
	ds_read_b128 v[170:173], v213 offset:2048
	ds_read_b128 v[174:177], v213 offset:3072
	ds_read_b128 v[194:197], v213 offset:4096
	ds_read_b128 v[200:203], v213 offset:5120
	ds_read_b128 v[204:207], v213 offset:6144
	ds_read_b128 v[214:217], v213 offset:7168
	global_load_lds_dwordx4 v186, s[30:31]
	s_add_i32 m0, s29, 0xe000
	s_nop 0
	global_load_lds_dwordx4 v188, s[30:31]
	s_waitcnt vmcnt(8)
	s_waitcnt lgkmcnt(0)
	s_setprio 1
	s_barrier
	v_mfma_f32_16x16x32_bf16 v[126:129], v[130:133], v[162:165], v[126:129]
	v_mfma_f32_16x16x32_bf16 v[122:125], v[138:141], v[162:165], v[122:125]
	v_mfma_f32_16x16x32_bf16 v[110:113], v[130:133], v[170:173], v[110:113]
	v_mfma_f32_16x16x32_bf16 v[106:109], v[138:141], v[170:173], v[106:109]
	v_mfma_f32_16x16x32_bf16 v[94:97], v[130:133], v[194:197], v[94:97]
	v_mfma_f32_16x16x32_bf16 v[90:93], v[138:141], v[194:197], v[90:93]
	v_mfma_f32_16x16x32_bf16 v[78:81], v[130:133], v[204:207], v[78:81]
	v_mfma_f32_16x16x32_bf16 v[74:77], v[138:141], v[204:207], v[74:77]
	v_mfma_f32_16x16x32_bf16 v[126:129], v[134:137], v[166:169], v[126:129]
	v_mfma_f32_16x16x32_bf16 v[122:125], v[142:145], v[166:169], v[122:125]
	v_mfma_f32_16x16x32_bf16 v[110:113], v[134:137], v[174:177], v[110:113]
	v_mfma_f32_16x16x32_bf16 v[106:109], v[142:145], v[174:177], v[106:109]
	v_mfma_f32_16x16x32_bf16 v[94:97], v[134:137], v[200:203], v[94:97]
	v_mfma_f32_16x16x32_bf16 v[90:93], v[142:145], v[200:203], v[90:93]
	v_mfma_f32_16x16x32_bf16 v[78:81], v[134:137], v[214:217], v[78:81]
	v_mfma_f32_16x16x32_bf16 v[74:77], v[142:145], v[214:217], v[74:77]
	v_mfma_f32_16x16x32_bf16 v[118:121], v[146:149], v[162:165], v[118:121]
	v_mfma_f32_16x16x32_bf16 v[114:117], v[154:157], v[162:165], v[114:117]
	v_mfma_f32_16x16x32_bf16 v[102:105], v[146:149], v[170:173], v[102:105]
	v_mfma_f32_16x16x32_bf16 v[98:101], v[154:157], v[170:173], v[98:101]
	v_mfma_f32_16x16x32_bf16 v[86:89], v[146:149], v[194:197], v[86:89]
	v_mfma_f32_16x16x32_bf16 v[82:85], v[154:157], v[194:197], v[82:85]
	v_mfma_f32_16x16x32_bf16 v[70:73], v[146:149], v[204:207], v[70:73]
	v_mfma_f32_16x16x32_bf16 v[66:69], v[154:157], v[204:207], v[66:69]
	v_mfma_f32_16x16x32_bf16 v[118:121], v[150:153], v[166:169], v[118:121]
	v_mfma_f32_16x16x32_bf16 v[114:117], v[158:161], v[166:169], v[114:117]
	v_mfma_f32_16x16x32_bf16 v[102:105], v[150:153], v[174:177], v[102:105]
	v_mfma_f32_16x16x32_bf16 v[98:101], v[158:161], v[174:177], v[98:101]
	v_mfma_f32_16x16x32_bf16 v[86:89], v[150:153], v[200:203], v[86:89]
	v_mfma_f32_16x16x32_bf16 v[82:85], v[158:161], v[200:203], v[82:85]
	v_mfma_f32_16x16x32_bf16 v[70:73], v[150:153], v[214:217], v[70:73]
	v_mfma_f32_16x16x32_bf16 v[66:69], v[158:161], v[214:217], v[66:69]
	s_barrier
	s_setprio 0
	s_add_i32 s57, s46, s38
	s_mov_b32 m0, s57
	ds_read_b128 v[162:165], v213 offset:16384
	ds_read_b128 v[166:169], v213 offset:17408
	ds_read_b128 v[170:173], v213 offset:18432
	ds_read_b128 v[174:177], v213 offset:19456
	ds_read_b128 v[194:197], v213 offset:20480
	ds_read_b128 v[200:203], v213 offset:21504
	ds_read_b128 v[204:207], v213 offset:22528
	ds_read_b128 v[214:217], v213 offset:23552
	global_load_lds_dwordx4 v180, s[34:35]
	s_add_i32 m0, s57, 0x2000
	s_add_u32 s58, s34, 0x80000
	s_addc_u32 s59, s35, 0
	s_add_i32 s57, s47, s38
	global_load_lds_dwordx4 v184, s[34:35]
	s_mov_b32 m0, s57
	s_nop 0
	global_load_lds_dwordx4 v180, s[58:59]
	s_add_i32 m0, s57, 0x2000
	s_nop 0
	global_load_lds_dwordx4 v184, s[58:59]
	s_waitcnt vmcnt(6)
	s_waitcnt lgkmcnt(0)
	s_setprio 1
	s_barrier
	v_mfma_f32_16x16x32_bf16 v[62:65], v[130:133], v[162:165], v[62:65]
	v_mfma_f32_16x16x32_bf16 v[58:61], v[138:141], v[162:165], v[58:61]
	v_mfma_f32_16x16x32_bf16 v[46:49], v[130:133], v[170:173], v[46:49]
	v_mfma_f32_16x16x32_bf16 v[42:45], v[138:141], v[170:173], v[42:45]
	v_mfma_f32_16x16x32_bf16 v[30:33], v[130:133], v[194:197], v[30:33]
	v_mfma_f32_16x16x32_bf16 v[26:29], v[138:141], v[194:197], v[26:29]
	v_mfma_f32_16x16x32_bf16 v[14:17], v[130:133], v[204:207], v[14:17]
	v_mfma_f32_16x16x32_bf16 v[10:13], v[138:141], v[204:207], v[10:13]
	v_mfma_f32_16x16x32_bf16 v[62:65], v[134:137], v[166:169], v[62:65]
	v_mfma_f32_16x16x32_bf16 v[58:61], v[142:145], v[166:169], v[58:61]
	v_mfma_f32_16x16x32_bf16 v[46:49], v[134:137], v[174:177], v[46:49]
	v_mfma_f32_16x16x32_bf16 v[42:45], v[142:145], v[174:177], v[42:45]
	v_mfma_f32_16x16x32_bf16 v[30:33], v[134:137], v[200:203], v[30:33]
	v_mfma_f32_16x16x32_bf16 v[26:29], v[142:145], v[200:203], v[26:29]
	v_mfma_f32_16x16x32_bf16 v[14:17], v[134:137], v[214:217], v[14:17]
	v_mfma_f32_16x16x32_bf16 v[10:13], v[142:145], v[214:217], v[10:13]
	v_mfma_f32_16x16x32_bf16 v[54:57], v[146:149], v[162:165], v[54:57]
	v_mfma_f32_16x16x32_bf16 v[50:53], v[154:157], v[162:165], v[50:53]
	v_mfma_f32_16x16x32_bf16 v[38:41], v[146:149], v[170:173], v[38:41]
	v_mfma_f32_16x16x32_bf16 v[34:37], v[154:157], v[170:173], v[34:37]
	v_mfma_f32_16x16x32_bf16 v[22:25], v[146:149], v[194:197], v[22:25]
	v_mfma_f32_16x16x32_bf16 v[18:21], v[154:157], v[194:197], v[18:21]
	v_mfma_f32_16x16x32_bf16 v[6:9], v[146:149], v[204:207], v[6:9]
	v_mfma_f32_16x16x32_bf16 v[2:5], v[154:157], v[204:207], v[2:5]
	v_mfma_f32_16x16x32_bf16 v[54:57], v[150:153], v[166:169], v[54:57]
	v_mfma_f32_16x16x32_bf16 v[50:53], v[158:161], v[166:169], v[50:53]
	v_mfma_f32_16x16x32_bf16 v[38:41], v[150:153], v[174:177], v[38:41]
	v_mfma_f32_16x16x32_bf16 v[34:37], v[158:161], v[174:177], v[34:37]
	v_mfma_f32_16x16x32_bf16 v[22:25], v[150:153], v[200:203], v[22:25]
	v_mfma_f32_16x16x32_bf16 v[18:21], v[158:161], v[200:203], v[18:21]
	v_mfma_f32_16x16x32_bf16 v[6:9], v[150:153], v[214:217], v[6:9]
	v_mfma_f32_16x16x32_bf16 v[2:5], v[158:161], v[214:217], v[2:5]
	s_barrier
; #define PG8_STAGE(bufoff, gbase, voff) do { _Pragma("unroll") for (int _i = 0; _i < 2; ++_i) \
;         __builtin_amdgcn_global_load_lds((const unsigned*)((const char*)(gbase) + (voff)[_i]), (PG8_LAS unsigned*)(lds + (bufoff) + ldsw + _i * 8192), 16, 0, 0); } while (0)
; #define PG8_LDA(dst, b, h) do { _Pragma("unroll") for (int m = 0; m < 4; ++m) _Pragma("unroll") for (int k = 0; k < 2; ++k) dst[m][k] = *(const PG8_LAS bf16x8*)(lds + PG8_SA(b, h) + aoff + m * 2048 + k * 1024); } while (0)
; #define PG8_LDB(dst, b, h) do { _Pragma("unroll") for (int n = 0; n < 2; ++n) _Pragma("unroll") for (int k = 0; k < 2; ++k) dst[n][k] = *(const PG8_LAS bf16x8*)(lds + PG8_SB(b, h) + boff + n * 2048 + k * 1024); } while (0)
; #define PG8_MMA(ai, bj, At, Bt) do { __builtin_amdgcn_s_setprio(1); _Pragma("unroll") for (int m = 0; m < 4; ++m) _Pragma("unroll") for (int n = 0; n < 2; ++n) _Pragma("unroll") for (int k = 0; k < 2; ++k) \
;         acc[ai][bj][m][n] = __builtin_amdgcn_mfma_f32_16x16x32_bf16(Bt[n][k], At[m][k], acc[ai][bj][m][n], 0, 0, 0); __builtin_amdgcn_s_setprio(0); } while (0)
; #define PG8_WAIT_V(n) asm volatile("s_waitcnt vmcnt(" #n ")" ::: "memory")
; #define PG8_WAIT_L(n) asm volatile("s_waitcnt lgkmcnt(" #n ")" ::: "memory")
; #define PG8_BAR __builtin_amdgcn_s_barrier()
; #define PG8_SCHED __builtin_amdgcn_sched_barrier(0)
; template <class Epi, class Sched, bool ALIGN_EPI = false, bool SP2 = false>
; __device__ __forceinline__ void gemm_phase(PG8_LAS unsigned char* lds, const Gemm g, const Sched& S, const Epi& E) {
;     ...
;             PG8_LDB(B0, 1, 0); PG8_LDB(B1, 1, 1); PG8_SCHED; PG8_LDA(At, 1, 0); PG8_STAGE(PG8_SA(0, 1), a2 + hstep, voffA);
;             PG8_WAIT_V(8); PG8_WAIT_L(0); PG8_BAR; PG8_MMA(0, 0, At, B0); PG8_MMA(0, 1, At, B1); PG8_BAR; PG8_SCHED;
;             PG8_LDA(At, 1, 1); PG8_STAGE(PG8_SB(1, 0), b3, voffB); PG8_STAGE(PG8_SB(1, 1), b3 + hstep, voffB); PG8_STAGE(PG8_SA(1, 0), a3, voffA);
;             PG8_WAIT_V(8); PG8_WAIT_L(0); PG8_BAR; PG8_MMA(1, 0, At, B0); PG8_MMA(1, 1, At, B1); PG8_BAR; PG8_SCHED;
;     ...
;         if constexpr (ALIGN_EPI) { if (wr == 0) PG8_BAR; }
	s_setprio 0
	s_mov_b32 m0, s29
	s_nop 0
	global_load_lds_dwordx4 v178, s[36:37]
	s_mov_b32 m0, s39
	s_nop 0
	global_load_lds_dwordx4 v182, s[36:37]
	s_add_i32 s57, 0, 0x18000
	s_add_i32 s58, 0, 0x1c000
	v_add_u32_e32 v142, s57, v199
	v_add_u32_e32 v158, s58, v199
	ds_read_b128 v[130:133], v142
	ds_read_b128 v[134:137], v142 offset:1024
	ds_read_b128 v[138:141], v142 offset:2048
	ds_read_b128 v[142:145], v142 offset:3072
	ds_read_b128 v[146:149], v158
	ds_read_b128 v[150:153], v158 offset:1024
	ds_read_b128 v[154:157], v158 offset:2048
	ds_read_b128 v[158:161], v158 offset:3072
	s_add_u32 s36, s36, 0x80000
	s_addc_u32 s37, s37, 0
	s_mov_b32 m0, s40
	ds_read_b128 v[162:165], v213 offset:32768
	ds_read_b128 v[166:169], v213 offset:33792
	ds_read_b128 v[170:173], v213 offset:34816
	ds_read_b128 v[174:177], v213 offset:35840
	ds_read_b128 v[194:197], v213 offset:36864
	ds_read_b128 v[200:203], v213 offset:37888
	ds_read_b128 v[204:207], v213 offset:38912
	ds_read_b128 v[214:217], v213 offset:39936
	global_load_lds_dwordx4 v178, s[36:37]
	s_mov_b32 m0, s41
	s_nop 0
	global_load_lds_dwordx4 v182, s[36:37]
	s_waitcnt vmcnt(8)
	s_waitcnt lgkmcnt(0)
	s_setprio 1
	s_barrier
	v_mfma_f32_16x16x32_bf16 v[126:129], v[130:133], v[162:165], v[126:129]
	v_mfma_f32_16x16x32_bf16 v[122:125], v[138:141], v[162:165], v[122:125]
	v_mfma_f32_16x16x32_bf16 v[110:113], v[130:133], v[170:173], v[110:113]
	v_mfma_f32_16x16x32_bf16 v[106:109], v[138:141], v[170:173], v[106:109]
	v_mfma_f32_16x16x32_bf16 v[94:97], v[130:133], v[194:197], v[94:97]
	v_mfma_f32_16x16x32_bf16 v[90:93], v[138:141], v[194:197], v[90:93]
	v_mfma_f32_16x16x32_bf16 v[78:81], v[130:133], v[204:207], v[78:81]
	v_mfma_f32_16x16x32_bf16 v[74:77], v[138:141], v[204:207], v[74:77]
	v_mfma_f32_16x16x32_bf16 v[126:129], v[134:137], v[166:169], v[126:129]
	v_mfma_f32_16x16x32_bf16 v[122:125], v[142:145], v[166:169], v[122:125]
	v_mfma_f32_16x16x32_bf16 v[110:113], v[134:137], v[174:177], v[110:113]
	v_mfma_f32_16x16x32_bf16 v[106:109], v[142:145], v[174:177], v[106:109]
	v_mfma_f32_16x16x32_bf16 v[94:97], v[134:137], v[200:203], v[94:97]
	v_mfma_f32_16x16x32_bf16 v[90:93], v[142:145], v[200:203], v[90:93]
	v_mfma_f32_16x16x32_bf16 v[78:81], v[134:137], v[214:217], v[78:81]
	v_mfma_f32_16x16x32_bf16 v[74:77], v[142:145], v[214:217], v[74:77]
	v_mfma_f32_16x16x32_bf16 v[118:121], v[146:149], v[162:165], v[118:121]
	v_mfma_f32_16x16x32_bf16 v[114:117], v[154:157], v[162:165], v[114:117]
	v_mfma_f32_16x16x32_bf16 v[102:105], v[146:149], v[170:173], v[102:105]
	v_mfma_f32_16x16x32_bf16 v[98:101], v[154:157], v[170:173], v[98:101]
	v_mfma_f32_16x16x32_bf16 v[86:89], v[146:149], v[194:197], v[86:89]
	v_mfma_f32_16x16x32_bf16 v[82:85], v[154:157], v[194:197], v[82:85]
	v_mfma_f32_16x16x32_bf16 v[70:73], v[146:149], v[204:207], v[70:73]
	v_mfma_f32_16x16x32_bf16 v[66:69], v[154:157], v[204:207], v[66:69]
	v_mfma_f32_16x16x32_bf16 v[118:121], v[150:153], v[166:169], v[118:121]
	v_mfma_f32_16x16x32_bf16 v[114:117], v[158:161], v[166:169], v[114:117]
	v_mfma_f32_16x16x32_bf16 v[102:105], v[150:153], v[174:177], v[102:105]
	v_mfma_f32_16x16x32_bf16 v[98:101], v[158:161], v[174:177], v[98:101]
	v_mfma_f32_16x16x32_bf16 v[86:89], v[150:153], v[200:203], v[86:89]
	v_mfma_f32_16x16x32_bf16 v[82:85], v[158:161], v[200:203], v[82:85]
	v_mfma_f32_16x16x32_bf16 v[70:73], v[150:153], v[214:217], v[70:73]
	v_mfma_f32_16x16x32_bf16 v[66:69], v[158:161], v[214:217], v[66:69]
	s_barrier
	s_setprio 0
	s_add_i32 s36, s57, s38
	s_add_u32 s34, s34, 0x80
	s_addc_u32 s35, s35, 0
	s_mov_b32 m0, s36
	ds_read_b128 v[162:165], v213 offset:49152
	ds_read_b128 v[166:169], v213 offset:50176
	ds_read_b128 v[170:173], v213 offset:51200
	ds_read_b128 v[174:177], v213 offset:52224
	ds_read_b128 v[194:197], v213 offset:53248
	ds_read_b128 v[200:203], v213 offset:54272
	ds_read_b128 v[204:207], v213 offset:55296
	ds_read_b128 v[214:217], v213 offset:56320
	global_load_lds_dwordx4 v180, s[34:35]
	s_add_i32 m0, s36, 0x2000
	s_add_i32 s36, s58, s38
	global_load_lds_dwordx4 v184, s[34:35]
	s_add_u32 s34, s34, 0x80000
	s_addc_u32 s35, s35, 0
	s_mov_b32 m0, s36
	s_nop 0
	global_load_lds_dwordx4 v180, s[34:35]
	s_add_i32 m0, s36, 0x2000
	s_nop 0
	global_load_lds_dwordx4 v184, s[34:35]
	s_waitcnt vmcnt(6)
	s_waitcnt lgkmcnt(0)
	s_setprio 1
	s_barrier
	v_mfma_f32_16x16x32_bf16 v[62:65], v[130:133], v[162:165], v[62:65]
	v_mfma_f32_16x16x32_bf16 v[58:61], v[138:141], v[162:165], v[58:61]
	v_mfma_f32_16x16x32_bf16 v[46:49], v[130:133], v[170:173], v[46:49]
	v_mfma_f32_16x16x32_bf16 v[42:45], v[138:141], v[170:173], v[42:45]
	v_mfma_f32_16x16x32_bf16 v[30:33], v[130:133], v[194:197], v[30:33]
	v_mfma_f32_16x16x32_bf16 v[26:29], v[138:141], v[194:197], v[26:29]
	v_mfma_f32_16x16x32_bf16 v[14:17], v[130:133], v[204:207], v[14:17]
	v_mfma_f32_16x16x32_bf16 v[10:13], v[138:141], v[204:207], v[10:13]
	v_mfma_f32_16x16x32_bf16 v[62:65], v[134:137], v[166:169], v[62:65]
	v_mfma_f32_16x16x32_bf16 v[58:61], v[142:145], v[166:169], v[58:61]
	v_mfma_f32_16x16x32_bf16 v[46:49], v[134:137], v[174:177], v[46:49]
	v_mfma_f32_16x16x32_bf16 v[42:45], v[142:145], v[174:177], v[42:45]
	v_mfma_f32_16x16x32_bf16 v[30:33], v[134:137], v[200:203], v[30:33]
	v_mfma_f32_16x16x32_bf16 v[26:29], v[142:145], v[200:203], v[26:29]
	v_mfma_f32_16x16x32_bf16 v[14:17], v[134:137], v[214:217], v[14:17]
	v_mfma_f32_16x16x32_bf16 v[10:13], v[142:145], v[214:217], v[10:13]
	v_mfma_f32_16x16x32_bf16 v[54:57], v[146:149], v[162:165], v[54:57]
	v_mfma_f32_16x16x32_bf16 v[50:53], v[154:157], v[162:165], v[50:53]
	v_mfma_f32_16x16x32_bf16 v[38:41], v[146:149], v[170:173], v[38:41]
	v_mfma_f32_16x16x32_bf16 v[34:37], v[154:157], v[170:173], v[34:37]
	v_mfma_f32_16x16x32_bf16 v[22:25], v[146:149], v[194:197], v[22:25]
	v_mfma_f32_16x16x32_bf16 v[18:21], v[154:157], v[194:197], v[18:21]
	v_mfma_f32_16x16x32_bf16 v[6:9], v[146:149], v[204:207], v[6:9]
	v_mfma_f32_16x16x32_bf16 v[2:5], v[154:157], v[204:207], v[2:5]
	v_mfma_f32_16x16x32_bf16 v[54:57], v[150:153], v[166:169], v[54:57]
	v_mfma_f32_16x16x32_bf16 v[50:53], v[158:161], v[166:169], v[50:53]
	v_mfma_f32_16x16x32_bf16 v[38:41], v[150:153], v[174:177], v[38:41]
	v_mfma_f32_16x16x32_bf16 v[34:37], v[158:161], v[174:177], v[34:37]
	v_mfma_f32_16x16x32_bf16 v[22:25], v[150:153], v[200:203], v[22:25]
	v_mfma_f32_16x16x32_bf16 v[18:21], v[158:161], v[200:203], v[18:21]
	v_mfma_f32_16x16x32_bf16 v[6:9], v[150:153], v[214:217], v[6:9]
	v_mfma_f32_16x16x32_bf16 v[2:5], v[158:161], v[214:217], v[2:5]
	s_barrier
	s_setprio 0
	s_add_i32 s56, s56, 2
	s_add_u32 s30, s30, 0x100
	s_addc_u32 s31, s31, 0
	s_add_u32 s52, s52, 0x100
	s_addc_u32 s53, s53, 0
	s_cmp_gt_u32 s56, 29
	s_cbranch_scc0 .LBB0_884
	s_and_b64 vcc, exec, s[10:11]
	s_cbranch_vccz .LBB0_887
	s_barrier

; #define PG8_STAGE(bufoff, gbase, voff) do { _Pragma("unroll") for (int _i = 0; _i < 2; ++_i) \
;         __builtin_amdgcn_global_load_lds((const unsigned*)((const char*)(gbase) + (voff)[_i]), (PG8_LAS unsigned*)(lds + (bufoff) + ldsw + _i * 8192), 16, 0, 0); } while (0)
; #define PG8_LDA(dst, b, h) do { _Pragma("unroll") for (int m = 0; m < 4; ++m) _Pragma("unroll") for (int k = 0; k < 2; ++k) dst[m][k] = *(const PG8_LAS bf16x8*)(lds + PG8_SA(b, h) + aoff + m * 2048 + k * 1024); } while (0)
; #define PG8_LDB(dst, b, h) do { _Pragma("unroll") for (int n = 0; n < 2; ++n) _Pragma("unroll") for (int k = 0; k < 2; ++k) dst[n][k] = *(const PG8_LAS bf16x8*)(lds + PG8_SB(b, h) + boff + n * 2048 + k * 1024); } while (0)
; #define PG8_MMA(ai, bj, At, Bt) do { __builtin_amdgcn_s_setprio(1); _Pragma("unroll") for (int m = 0; m < 4; ++m) _Pragma("unroll") for (int n = 0; n < 2; ++n) _Pragma("unroll") for (int k = 0; k < 2; ++k) \
;         acc[ai][bj][m][n] = __builtin_amdgcn_mfma_f32_16x16x32_bf16(Bt[n][k], At[m][k], acc[ai][bj][m][n], 0, 0, 0); __builtin_amdgcn_s_setprio(0); } while (0)
; #define PG8_WAIT_V(n) asm volatile("s_waitcnt vmcnt(" #n ")" ::: "memory")
; #define PG8_BAR __builtin_amdgcn_s_barrier()
; template <class Epi, class Sched, bool ALIGN_EPI = false, bool SP2 = false>
; __device__ __forceinline__ void gemm_phase(PG8_LAS unsigned char* lds, const Gemm g, const Sched& S, const Epi& E) {
;     ...
;         for (int t = 0; t < nt; t += 2) {
;             const bool last = (t == nt - 2);
;             const char* a1 = cA + (size_t)(t + 1) * kstep;
;             const char* a2 = last ? nA : cA + (size_t)(t + 2) * kstep; const char* b2 = last ? nB : cB + (size_t)(t + 2) * kstep;
;             const char* a3 = a2 + kstep; const char* b3 = b2 + kstep;
;             if (last && has_next) S.a_ready(nxt);
;             if constexpr (SP2) {
;             PG8_LDB(B0, 0, 0); PG8_LDB(B1, 0, 1); PG8_SCHED; PG8_LDA(At, 0, 0); PG8_STAGE(PG8_SA(1, 1), a1 + hstep, voffA);
;             PG8_WAIT_V(8); PG8_WAIT_L(0); PG8_BAR; PG8_MMA(0, 0, At, B0); PG8_MMA(0, 1, At, B1); PG8_BAR; PG8_SCHED;
;             PG8_LDA(At, 0, 1); PG8_STAGE(PG8_SB(0, 0), b2, voffB); PG8_STAGE(PG8_SB(0, 1), b2 + hstep, voffB); PG8_STAGE(PG8_SA(0, 0), a2, voffA);
;             PG8_WAIT_V(8); PG8_WAIT_L(0); PG8_BAR; PG8_MMA(1, 0, At, B0); PG8_MMA(1, 1, At, B1); PG8_BAR; PG8_SCHED;
.LBB0_959:
	s_add_u32 s30, s28, 0xfff00000
	s_addc_u32 s31, s29, -1
	s_mov_b32 m0, s41
	s_nop 0
	global_load_lds_dwordx4 v138, s[30:31]
	s_mov_b32 m0, s42
	s_nop 0
	global_load_lds_dwordx4 v142, s[30:31]
	s_add_u32 s30, s30, 0x80
	s_addc_u32 s31, s31, 0
	ds_read_b128 v[130:133], v164
	ds_read_b128 v[134:137], v164 offset:1024
	ds_read_b128 v[154:157], v164 offset:2048
	ds_read_b128 v[158:161], v164 offset:3072
	ds_read_b128 v[168:171], v165
	ds_read_b128 v[172:175], v165 offset:1024
	ds_read_b128 v[176:179], v165 offset:2048
	ds_read_b128 v[180:183], v165 offset:3072
	s_cmp_eq_u32 s51, 60
	s_cselect_b32 s35, s13, s31
	s_cselect_b32 s34, s47, s30
	s_cselect_b32 s31, s11, s50
	s_cselect_b32 s30, s48, s49
	s_add_i32 m0, s27, 0xc000
	ds_read_b128 v[184:187], v166
	ds_read_b128 v[188:191], v166 offset:1024
	ds_read_b128 v[192:195], v166 offset:2048
	ds_read_b128 v[200:203], v166 offset:3072
	ds_read_b128 v[204:207], v166 offset:4096
	ds_read_b128 v[208:211], v166 offset:5120
	ds_read_b128 v[212:215], v166 offset:6144
	ds_read_b128 v[216:219], v166 offset:7168
	global_load_lds_dwordx4 v146, s[28:29]
	s_add_i32 m0, s27, 0xe000
	s_nop 0
	global_load_lds_dwordx4 v148, s[28:29]
	s_waitcnt vmcnt(8)
	s_waitcnt lgkmcnt(0)
	s_setprio 1
	s_barrier
	v_mfma_f32_16x16x32_bf16 v[126:129], v[130:133], v[184:187], v[126:129]
	v_mfma_f32_16x16x32_bf16 v[122:125], v[154:157], v[184:187], v[122:125]
	v_mfma_f32_16x16x32_bf16 v[118:121], v[130:133], v[192:195], v[118:121]
	v_mfma_f32_16x16x32_bf16 v[114:117], v[154:157], v[192:195], v[114:117]
	v_mfma_f32_16x16x32_bf16 v[110:113], v[130:133], v[204:207], v[110:113]
	v_mfma_f32_16x16x32_bf16 v[102:105], v[154:157], v[204:207], v[102:105]
	v_mfma_f32_16x16x32_bf16 v[82:85], v[130:133], v[212:215], v[82:85]
	v_mfma_f32_16x16x32_bf16 v[74:77], v[154:157], v[212:215], v[74:77]
	v_mfma_f32_16x16x32_bf16 v[126:129], v[134:137], v[188:191], v[126:129]
	v_mfma_f32_16x16x32_bf16 v[122:125], v[158:161], v[188:191], v[122:125]
	v_mfma_f32_16x16x32_bf16 v[118:121], v[134:137], v[200:203], v[118:121]
	v_mfma_f32_16x16x32_bf16 v[114:117], v[158:161], v[200:203], v[114:117]
	v_mfma_f32_16x16x32_bf16 v[110:113], v[134:137], v[208:211], v[110:113]
	v_mfma_f32_16x16x32_bf16 v[102:105], v[158:161], v[208:211], v[102:105]
	v_mfma_f32_16x16x32_bf16 v[82:85], v[134:137], v[216:219], v[82:85]
	v_mfma_f32_16x16x32_bf16 v[74:77], v[158:161], v[216:219], v[74:77]
	v_mfma_f32_16x16x32_bf16 v[106:109], v[168:171], v[184:187], v[106:109]
	v_mfma_f32_16x16x32_bf16 v[98:101], v[176:179], v[184:187], v[98:101]
	v_mfma_f32_16x16x32_bf16 v[94:97], v[168:171], v[192:195], v[94:97]
	v_mfma_f32_16x16x32_bf16 v[90:93], v[176:179], v[192:195], v[90:93]
	v_mfma_f32_16x16x32_bf16 v[86:89], v[168:171], v[204:207], v[86:89]
	v_mfma_f32_16x16x32_bf16 v[78:81], v[176:179], v[204:207], v[78:81]
	v_mfma_f32_16x16x32_bf16 v[70:73], v[168:171], v[212:215], v[70:73]
	v_mfma_f32_16x16x32_bf16 v[66:69], v[176:179], v[212:215], v[66:69]
	v_mfma_f32_16x16x32_bf16 v[106:109], v[172:175], v[188:191], v[106:109]
	v_mfma_f32_16x16x32_bf16 v[98:101], v[180:183], v[188:191], v[98:101]
	v_mfma_f32_16x16x32_bf16 v[94:97], v[172:175], v[200:203], v[94:97]
	v_mfma_f32_16x16x32_bf16 v[90:93], v[180:183], v[200:203], v[90:93]
	v_mfma_f32_16x16x32_bf16 v[86:89], v[172:175], v[208:211], v[86:89]
	v_mfma_f32_16x16x32_bf16 v[78:81], v[180:183], v[208:211], v[78:81]
	v_mfma_f32_16x16x32_bf16 v[70:73], v[172:175], v[216:219], v[70:73]
	v_mfma_f32_16x16x32_bf16 v[66:69], v[180:183], v[216:219], v[66:69]
	s_barrier
	s_setprio 0
	s_add_i32 s52, s44, s36
	s_mov_b32 m0, s52
	ds_read_b128 v[184:187], v166 offset:16384
	ds_read_b128 v[188:191], v166 offset:17408
	ds_read_b128 v[192:195], v166 offset:18432
	ds_read_b128 v[200:203], v166 offset:19456
	ds_read_b128 v[204:207], v166 offset:20480
	ds_read_b128 v[208:211], v166 offset:21504
	ds_read_b128 v[212:215], v166 offset:22528
	ds_read_b128 v[216:219], v166 offset:23552
	global_load_lds_dwordx4 v140, s[30:31]
	s_add_i32 m0, s52, 0x2000
	s_add_u32 s52, s30, 0x100000
	s_addc_u32 s53, s31, 0
	s_add_i32 s54, s45, s36
	global_load_lds_dwordx4 v144, s[30:31]
	s_mov_b32 m0, s54
	s_nop 0
	global_load_lds_dwordx4 v140, s[52:53]
	s_add_i32 m0, s54, 0x2000
	s_nop 0
	global_load_lds_dwordx4 v144, s[52:53]
	s_waitcnt vmcnt(6)
	s_waitcnt lgkmcnt(0)
	s_setprio 1
	s_barrier
	v_mfma_f32_16x16x32_bf16 v[62:65], v[130:133], v[184:187], v[62:65]
	v_mfma_f32_16x16x32_bf16 v[58:61], v[154:157], v[184:187], v[58:61]
	v_mfma_f32_16x16x32_bf16 v[50:53], v[130:133], v[192:195], v[50:53]
	v_mfma_f32_16x16x32_bf16 v[42:45], v[154:157], v[192:195], v[42:45]
	v_mfma_f32_16x16x32_bf16 v[34:37], v[130:133], v[204:207], v[34:37]
	v_mfma_f32_16x16x32_bf16 v[26:29], v[154:157], v[204:207], v[26:29]
	v_mfma_f32_16x16x32_bf16 v[18:21], v[130:133], v[212:215], v[18:21]
	v_mfma_f32_16x16x32_bf16 v[10:13], v[154:157], v[212:215], v[10:13]
	v_mfma_f32_16x16x32_bf16 v[62:65], v[134:137], v[188:191], v[62:65]
	v_mfma_f32_16x16x32_bf16 v[58:61], v[158:161], v[188:191], v[58:61]
	v_mfma_f32_16x16x32_bf16 v[50:53], v[134:137], v[200:203], v[50:53]
	v_mfma_f32_16x16x32_bf16 v[42:45], v[158:161], v[200:203], v[42:45]
	v_mfma_f32_16x16x32_bf16 v[34:37], v[134:137], v[208:211], v[34:37]
	v_mfma_f32_16x16x32_bf16 v[26:29], v[158:161], v[208:211], v[26:29]
	v_mfma_f32_16x16x32_bf16 v[18:21], v[134:137], v[216:219], v[18:21]
	v_mfma_f32_16x16x32_bf16 v[10:13], v[158:161], v[216:219], v[10:13]
	v_mfma_f32_16x16x32_bf16 v[54:57], v[168:171], v[184:187], v[54:57]
	v_mfma_f32_16x16x32_bf16 v[46:49], v[176:179], v[184:187], v[46:49]
	v_mfma_f32_16x16x32_bf16 v[38:41], v[168:171], v[192:195], v[38:41]
	v_mfma_f32_16x16x32_bf16 v[30:33], v[176:179], v[192:195], v[30:33]
	v_mfma_f32_16x16x32_bf16 v[22:25], v[168:171], v[204:207], v[22:25]
	v_mfma_f32_16x16x32_bf16 v[14:17], v[176:179], v[204:207], v[14:17]
	v_mfma_f32_16x16x32_bf16 v[6:9], v[168:171], v[212:215], v[6:9]
	v_mfma_f32_16x16x32_bf16 v[2:5], v[176:179], v[212:215], v[2:5]
	v_mfma_f32_16x16x32_bf16 v[54:57], v[172:175], v[188:191], v[54:57]
	v_mfma_f32_16x16x32_bf16 v[46:49], v[180:183], v[188:191], v[46:49]
	v_mfma_f32_16x16x32_bf16 v[38:41], v[172:175], v[200:203], v[38:41]
	v_mfma_f32_16x16x32_bf16 v[30:33], v[180:183], v[200:203], v[30:33]
	v_mfma_f32_16x16x32_bf16 v[22:25], v[172:175], v[208:211], v[22:25]
	v_mfma_f32_16x16x32_bf16 v[14:17], v[180:183], v[208:211], v[14:17]
	v_mfma_f32_16x16x32_bf16 v[6:9], v[172:175], v[216:219], v[6:9]
	v_mfma_f32_16x16x32_bf16 v[2:5], v[180:183], v[216:219], v[2:5]
	s_barrier
; #define PG8_STAGE(bufoff, gbase, voff) do { _Pragma("unroll") for (int _i = 0; _i < 2; ++_i) \
;         __builtin_amdgcn_global_load_lds((const unsigned*)((const char*)(gbase) + (voff)[_i]), (PG8_LAS unsigned*)(lds + (bufoff) + ldsw + _i * 8192), 16, 0, 0); } while (0)
; #define PG8_LDA(dst, b, h) do { _Pragma("unroll") for (int m = 0; m < 4; ++m) _Pragma("unroll") for (int k = 0; k < 2; ++k) dst[m][k] = *(const PG8_LAS bf16x8*)(lds + PG8_SA(b, h) + aoff + m * 2048 + k * 1024); } while (0)
; #define PG8_LDB(dst, b, h) do { _Pragma("unroll") for (int n = 0; n < 2; ++n) _Pragma("unroll") for (int k = 0; k < 2; ++k) dst[n][k] = *(const PG8_LAS bf16x8*)(lds + PG8_SB(b, h) + boff + n * 2048 + k * 1024); } while (0)
; #define PG8_MMA(ai, bj, At, Bt) do { __builtin_amdgcn_s_setprio(1); _Pragma("unroll") for (int m = 0; m < 4; ++m) _Pragma("unroll") for (int n = 0; n < 2; ++n) _Pragma("unroll") for (int k = 0; k < 2; ++k) \
;         acc[ai][bj][m][n] = __builtin_amdgcn_mfma_f32_16x16x32_bf16(Bt[n][k], At[m][k], acc[ai][bj][m][n], 0, 0, 0); __builtin_amdgcn_s_setprio(0); } while (0)
; #define PG8_WAIT_V(n) asm volatile("s_waitcnt vmcnt(" #n ")" ::: "memory")
; #define PG8_WAIT_L(n) asm volatile("s_waitcnt lgkmcnt(" #n ")" ::: "memory")
; #define PG8_BAR __builtin_amdgcn_s_barrier()
; #define PG8_SCHED __builtin_amdgcn_sched_barrier(0)
; template <class Epi, class Sched, bool ALIGN_EPI = false, bool SP2 = false>
; __device__ __forceinline__ void gemm_phase(PG8_LAS unsigned char* lds, const Gemm g, const Sched& S, const Epi& E) {
;     ...
;             PG8_LDB(B0, 1, 0); PG8_LDB(B1, 1, 1); PG8_SCHED; PG8_LDA(At, 1, 0); PG8_STAGE(PG8_SA(0, 1), a2 + hstep, voffA);
;             PG8_WAIT_V(8); PG8_WAIT_L(0); PG8_BAR; PG8_MMA(0, 0, At, B0); PG8_MMA(0, 1, At, B1); PG8_BAR; PG8_SCHED;
;             PG8_LDA(At, 1, 1); PG8_STAGE(PG8_SB(1, 0), b3, voffB); PG8_STAGE(PG8_SB(1, 1), b3 + hstep, voffB); PG8_STAGE(PG8_SA(1, 0), a3, voffA);
;             PG8_WAIT_V(8); PG8_WAIT_L(0); PG8_BAR; PG8_MMA(1, 0, At, B0); PG8_MMA(1, 1, At, B1); PG8_BAR; PG8_SCHED;
;     ...
;         if constexpr (ALIGN_EPI) { if (wr == 0) PG8_BAR; }
	s_setprio 0
	s_mov_b32 m0, s27
	s_nop 0
	global_load_lds_dwordx4 v138, s[34:35]
	s_mov_b32 m0, s37
	s_nop 0
	global_load_lds_dwordx4 v142, s[34:35]
	s_add_i32 s52, 0, 0x18000
	s_add_i32 s53, 0, 0x1c000
	v_add_u32_e32 v158, s52, v162
	v_add_u32_e32 v167, s53, v162
	ds_read_b128 v[130:133], v158
	ds_read_b128 v[134:137], v158 offset:1024
	ds_read_b128 v[154:157], v158 offset:2048
	ds_read_b128 v[158:161], v158 offset:3072
	ds_read_b128 v[168:171], v167
	ds_read_b128 v[172:175], v167 offset:1024
	ds_read_b128 v[176:179], v167 offset:2048
	ds_read_b128 v[180:183], v167 offset:3072
	s_add_u32 s34, s34, 0x100000
	s_addc_u32 s35, s35, 0
	s_mov_b32 m0, s38
	ds_read_b128 v[184:187], v166 offset:32768
	ds_read_b128 v[188:191], v166 offset:33792
	ds_read_b128 v[192:195], v166 offset:34816
	ds_read_b128 v[200:203], v166 offset:35840
	ds_read_b128 v[204:207], v166 offset:36864
	ds_read_b128 v[208:211], v166 offset:37888
	ds_read_b128 v[212:215], v166 offset:38912
	ds_read_b128 v[216:219], v166 offset:39936
	global_load_lds_dwordx4 v138, s[34:35]
	s_mov_b32 m0, s39
	s_nop 0
	global_load_lds_dwordx4 v142, s[34:35]
	s_waitcnt vmcnt(8)
	s_waitcnt lgkmcnt(0)
	s_setprio 1
	s_barrier
	v_mfma_f32_16x16x32_bf16 v[126:129], v[130:133], v[184:187], v[126:129]
	v_mfma_f32_16x16x32_bf16 v[122:125], v[154:157], v[184:187], v[122:125]
	v_mfma_f32_16x16x32_bf16 v[118:121], v[130:133], v[192:195], v[118:121]
	v_mfma_f32_16x16x32_bf16 v[114:117], v[154:157], v[192:195], v[114:117]
	v_mfma_f32_16x16x32_bf16 v[110:113], v[130:133], v[204:207], v[110:113]
	v_mfma_f32_16x16x32_bf16 v[102:105], v[154:157], v[204:207], v[102:105]
	v_mfma_f32_16x16x32_bf16 v[82:85], v[130:133], v[212:215], v[82:85]
	v_mfma_f32_16x16x32_bf16 v[74:77], v[154:157], v[212:215], v[74:77]
	v_mfma_f32_16x16x32_bf16 v[126:129], v[134:137], v[188:191], v[126:129]
	v_mfma_f32_16x16x32_bf16 v[122:125], v[158:161], v[188:191], v[122:125]
	v_mfma_f32_16x16x32_bf16 v[118:121], v[134:137], v[200:203], v[118:121]
	v_mfma_f32_16x16x32_bf16 v[114:117], v[158:161], v[200:203], v[114:117]
	v_mfma_f32_16x16x32_bf16 v[110:113], v[134:137], v[208:211], v[110:113]
	v_mfma_f32_16x16x32_bf16 v[102:105], v[158:161], v[208:211], v[102:105]
	v_mfma_f32_16x16x32_bf16 v[82:85], v[134:137], v[216:219], v[82:85]
	v_mfma_f32_16x16x32_bf16 v[74:77], v[158:161], v[216:219], v[74:77]
	v_mfma_f32_16x16x32_bf16 v[106:109], v[168:171], v[184:187], v[106:109]
	v_mfma_f32_16x16x32_bf16 v[98:101], v[176:179], v[184:187], v[98:101]
	v_mfma_f32_16x16x32_bf16 v[94:97], v[168:171], v[192:195], v[94:97]
	v_mfma_f32_16x16x32_bf16 v[90:93], v[176:179], v[192:195], v[90:93]
	v_mfma_f32_16x16x32_bf16 v[86:89], v[168:171], v[204:207], v[86:89]
	v_mfma_f32_16x16x32_bf16 v[78:81], v[176:179], v[204:207], v[78:81]
	v_mfma_f32_16x16x32_bf16 v[70:73], v[168:171], v[212:215], v[70:73]
	v_mfma_f32_16x16x32_bf16 v[66:69], v[176:179], v[212:215], v[66:69]
	v_mfma_f32_16x16x32_bf16 v[106:109], v[172:175], v[188:191], v[106:109]
	v_mfma_f32_16x16x32_bf16 v[98:101], v[180:183], v[188:191], v[98:101]
	v_mfma_f32_16x16x32_bf16 v[94:97], v[172:175], v[200:203], v[94:97]
	v_mfma_f32_16x16x32_bf16 v[90:93], v[180:183], v[200:203], v[90:93]
	v_mfma_f32_16x16x32_bf16 v[86:89], v[172:175], v[208:211], v[86:89]
	v_mfma_f32_16x16x32_bf16 v[78:81], v[180:183], v[208:211], v[78:81]
	v_mfma_f32_16x16x32_bf16 v[70:73], v[172:175], v[216:219], v[70:73]
	v_mfma_f32_16x16x32_bf16 v[66:69], v[180:183], v[216:219], v[66:69]
	s_barrier
	s_setprio 0
	s_add_i32 s34, s52, s36
	s_add_u32 s30, s30, 0x80
	s_addc_u32 s31, s31, 0
	s_mov_b32 m0, s34
	ds_read_b128 v[184:187], v166 offset:49152
	ds_read_b128 v[188:191], v166 offset:50176
	ds_read_b128 v[192:195], v166 offset:51200
	ds_read_b128 v[200:203], v166 offset:52224
	ds_read_b128 v[204:207], v166 offset:53248
	ds_read_b128 v[208:211], v166 offset:54272
	ds_read_b128 v[212:215], v166 offset:55296
	ds_read_b128 v[216:219], v166 offset:56320
	global_load_lds_dwordx4 v140, s[30:31]
	s_add_i32 m0, s34, 0x2000
	s_add_i32 s34, s53, s36
	global_load_lds_dwordx4 v144, s[30:31]
	s_add_u32 s30, s30, 0x100000
	s_addc_u32 s31, s31, 0
	s_mov_b32 m0, s34
	s_nop 0
	global_load_lds_dwordx4 v140, s[30:31]
	s_add_i32 m0, s34, 0x2000
	s_nop 0
	global_load_lds_dwordx4 v144, s[30:31]
	s_waitcnt vmcnt(6)
	s_waitcnt lgkmcnt(0)
	s_setprio 1
	s_barrier
	v_mfma_f32_16x16x32_bf16 v[62:65], v[130:133], v[184:187], v[62:65]
	v_mfma_f32_16x16x32_bf16 v[58:61], v[154:157], v[184:187], v[58:61]
	v_mfma_f32_16x16x32_bf16 v[50:53], v[130:133], v[192:195], v[50:53]
	v_mfma_f32_16x16x32_bf16 v[42:45], v[154:157], v[192:195], v[42:45]
	v_mfma_f32_16x16x32_bf16 v[34:37], v[130:133], v[204:207], v[34:37]
	v_mfma_f32_16x16x32_bf16 v[26:29], v[154:157], v[204:207], v[26:29]
	v_mfma_f32_16x16x32_bf16 v[18:21], v[130:133], v[212:215], v[18:21]
	v_mfma_f32_16x16x32_bf16 v[10:13], v[154:157], v[212:215], v[10:13]
	v_mfma_f32_16x16x32_bf16 v[62:65], v[134:137], v[188:191], v[62:65]
	v_mfma_f32_16x16x32_bf16 v[58:61], v[158:161], v[188:191], v[58:61]
	v_mfma_f32_16x16x32_bf16 v[50:53], v[134:137], v[200:203], v[50:53]
	v_mfma_f32_16x16x32_bf16 v[42:45], v[158:161], v[200:203], v[42:45]
	v_mfma_f32_16x16x32_bf16 v[34:37], v[134:137], v[208:211], v[34:37]
	v_mfma_f32_16x16x32_bf16 v[26:29], v[158:161], v[208:211], v[26:29]
	v_mfma_f32_16x16x32_bf16 v[18:21], v[134:137], v[216:219], v[18:21]
	v_mfma_f32_16x16x32_bf16 v[10:13], v[158:161], v[216:219], v[10:13]
	v_mfma_f32_16x16x32_bf16 v[54:57], v[168:171], v[184:187], v[54:57]
	v_mfma_f32_16x16x32_bf16 v[46:49], v[176:179], v[184:187], v[46:49]
	v_mfma_f32_16x16x32_bf16 v[38:41], v[168:171], v[192:195], v[38:41]
	v_mfma_f32_16x16x32_bf16 v[30:33], v[176:179], v[192:195], v[30:33]
	v_mfma_f32_16x16x32_bf16 v[22:25], v[168:171], v[204:207], v[22:25]
	v_mfma_f32_16x16x32_bf16 v[14:17], v[176:179], v[204:207], v[14:17]
	v_mfma_f32_16x16x32_bf16 v[6:9], v[168:171], v[212:215], v[6:9]
	v_mfma_f32_16x16x32_bf16 v[2:5], v[176:179], v[212:215], v[2:5]
	v_mfma_f32_16x16x32_bf16 v[54:57], v[172:175], v[188:191], v[54:57]
	v_mfma_f32_16x16x32_bf16 v[46:49], v[180:183], v[188:191], v[46:49]
	v_mfma_f32_16x16x32_bf16 v[38:41], v[172:175], v[200:203], v[38:41]
	v_mfma_f32_16x16x32_bf16 v[30:33], v[180:183], v[200:203], v[30:33]
	v_mfma_f32_16x16x32_bf16 v[22:25], v[172:175], v[208:211], v[22:25]
	v_mfma_f32_16x16x32_bf16 v[14:17], v[180:183], v[208:211], v[14:17]
	v_mfma_f32_16x16x32_bf16 v[6:9], v[172:175], v[216:219], v[6:9]
	v_mfma_f32_16x16x32_bf16 v[2:5], v[180:183], v[216:219], v[2:5]
	s_barrier
	s_setprio 0
	s_add_i32 s51, s51, 2
	s_add_u32 s28, s28, 0x100
	s_addc_u32 s29, s29, 0
	s_add_u32 s49, s49, 0x100
	s_addc_u32 s50, s50, 0
	s_cmp_gt_u32 s51, 61
	s_cbranch_scc0 .LBB0_959
	s_and_b64 vcc, exec, s[8:9]
	s_cbranch_vccz .LBB0_962
	s_barrier

; #define PG8_STAGE(bufoff, gbase, voff) do { _Pragma("unroll") for (int _i = 0; _i < 2; ++_i) \
;         __builtin_amdgcn_global_load_lds((const unsigned*)((const char*)(gbase) + (voff)[_i]), (PG8_LAS unsigned*)(lds + (bufoff) + ldsw + _i * 8192), 16, 0, 0); } while (0)
; #define PG8_LDA(dst, b, h) do { _Pragma("unroll") for (int m = 0; m < 4; ++m) _Pragma("unroll") for (int k = 0; k < 2; ++k) dst[m][k] = *(const PG8_LAS bf16x8*)(lds + PG8_SA(b, h) + aoff + m * 2048 + k * 1024); } while (0)
; #define PG8_LDB(dst, b, h) do { _Pragma("unroll") for (int n = 0; n < 2; ++n) _Pragma("unroll") for (int k = 0; k < 2; ++k) dst[n][k] = *(const PG8_LAS bf16x8*)(lds + PG8_SB(b, h) + boff + n * 2048 + k * 1024); } while (0)
; #define PG8_MMA(ai, bj, At, Bt) do { __builtin_amdgcn_s_setprio(1); _Pragma("unroll") for (int m = 0; m < 4; ++m) _Pragma("unroll") for (int n = 0; n < 2; ++n) _Pragma("unroll") for (int k = 0; k < 2; ++k) \
;         acc[ai][bj][m][n] = __builtin_amdgcn_mfma_f32_16x16x32_bf16(Bt[n][k], At[m][k], acc[ai][bj][m][n], 0, 0, 0); __builtin_amdgcn_s_setprio(0); } while (0)
; #define PG8_WAIT_V(n) asm volatile("s_waitcnt vmcnt(" #n ")" ::: "memory")
; #define PG8_BAR __builtin_amdgcn_s_barrier()
; template <class Epi, class Sched, bool ALIGN_EPI = false, bool SP2 = false>
; __device__ __forceinline__ void gemm_phase(PG8_LAS unsigned char* lds, const Gemm g, const Sched& S, const Epi& E) {
;     ...
;         for (int t = 0; t < nt; t += 2) {
;             const bool last = (t == nt - 2);
;             const char* a1 = cA + (size_t)(t + 1) * kstep;
;             const char* a2 = last ? nA : cA + (size_t)(t + 2) * kstep; const char* b2 = last ? nB : cB + (size_t)(t + 2) * kstep;
;             const char* a3 = a2 + kstep; const char* b3 = b2 + kstep;
;             if (last && has_next) S.a_ready(nxt);
;             if constexpr (SP2) {
;             PG8_LDB(B0, 0, 0); PG8_LDB(B1, 0, 1); PG8_SCHED; PG8_LDA(At, 0, 0); PG8_STAGE(PG8_SA(1, 1), a1 + hstep, voffA);
;             PG8_WAIT_V(8); PG8_WAIT_L(0); PG8_BAR; PG8_MMA(0, 0, At, B0); PG8_MMA(0, 1, At, B1); PG8_BAR; PG8_SCHED;
;             PG8_LDA(At, 0, 1); PG8_STAGE(PG8_SB(0, 0), b2, voffB); PG8_STAGE(PG8_SB(0, 1), b2 + hstep, voffB); PG8_STAGE(PG8_SA(0, 0), a2, voffA);
;             PG8_WAIT_V(8); PG8_WAIT_L(0); PG8_BAR; PG8_MMA(1, 0, At, B0); PG8_MMA(1, 1, At, B1); PG8_BAR; PG8_SCHED;
.LBB0_1081:
	s_add_u32 s34, s30, 0xfff00000
	s_addc_u32 s35, s31, -1
	s_mov_b32 m0, s44
	s_nop 0
	global_load_lds_dwordx4 v136, s[34:35]
	s_mov_b32 m0, s45
	s_nop 0
	global_load_lds_dwordx4 v132, s[34:35]
	s_add_u32 s34, s34, 0x80
	s_addc_u32 s35, s35, 0
	ds_read_b128 v[154:157], v150
	ds_read_b128 v[158:161], v150 offset:1024
	ds_read_b128 v[162:165], v150 offset:2048
	ds_read_b128 v[166:169], v150 offset:3072
	ds_read_b128 v[170:173], v151
	ds_read_b128 v[174:177], v151 offset:1024
	ds_read_b128 v[178:181], v151 offset:2048
	ds_read_b128 v[182:185], v151 offset:3072
	s_cmp_eq_u32 s55, 60
	s_cselect_b32 s37, s15, s35
	s_cselect_b32 s36, s51, s34
	s_cselect_b32 s35, s13, s54
	s_cselect_b32 s34, s52, s53
	s_add_i32 m0, s29, 0xc000
	ds_read_b128 v[186:189], v152
	ds_read_b128 v[190:193], v152 offset:1024
	ds_read_b128 v[194:197], v152 offset:2048
	ds_read_b128 v[200:203], v152 offset:3072
	ds_read_b128 v[204:207], v152 offset:4096
	ds_read_b128 v[208:211], v152 offset:5120
	ds_read_b128 v[212:215], v152 offset:6144
	ds_read_b128 v[216:219], v152 offset:7168
	global_load_lds_dwordx4 v138, s[30:31]
	s_add_i32 m0, s29, 0xe000
	s_nop 0
	global_load_lds_dwordx4 v140, s[30:31]
	s_waitcnt vmcnt(8)
	s_waitcnt lgkmcnt(0)
	s_setprio 1
	s_barrier
	v_mfma_f32_16x16x32_bf16 v[126:129], v[154:157], v[186:189], v[126:129]
	v_mfma_f32_16x16x32_bf16 v[122:125], v[162:165], v[186:189], v[122:125]
	v_mfma_f32_16x16x32_bf16 v[110:113], v[154:157], v[194:197], v[110:113]
	v_mfma_f32_16x16x32_bf16 v[106:109], v[162:165], v[194:197], v[106:109]
	v_mfma_f32_16x16x32_bf16 v[94:97], v[154:157], v[204:207], v[94:97]
	v_mfma_f32_16x16x32_bf16 v[90:93], v[162:165], v[204:207], v[90:93]
	v_mfma_f32_16x16x32_bf16 v[78:81], v[154:157], v[212:215], v[78:81]
	v_mfma_f32_16x16x32_bf16 v[74:77], v[162:165], v[212:215], v[74:77]
	v_mfma_f32_16x16x32_bf16 v[126:129], v[158:161], v[190:193], v[126:129]
	v_mfma_f32_16x16x32_bf16 v[122:125], v[166:169], v[190:193], v[122:125]
	v_mfma_f32_16x16x32_bf16 v[110:113], v[158:161], v[200:203], v[110:113]
	v_mfma_f32_16x16x32_bf16 v[106:109], v[166:169], v[200:203], v[106:109]
	v_mfma_f32_16x16x32_bf16 v[94:97], v[158:161], v[208:211], v[94:97]
	v_mfma_f32_16x16x32_bf16 v[90:93], v[166:169], v[208:211], v[90:93]
	v_mfma_f32_16x16x32_bf16 v[78:81], v[158:161], v[216:219], v[78:81]
	v_mfma_f32_16x16x32_bf16 v[74:77], v[166:169], v[216:219], v[74:77]
	v_mfma_f32_16x16x32_bf16 v[118:121], v[170:173], v[186:189], v[118:121]
	v_mfma_f32_16x16x32_bf16 v[114:117], v[178:181], v[186:189], v[114:117]
	v_mfma_f32_16x16x32_bf16 v[102:105], v[170:173], v[194:197], v[102:105]
	v_mfma_f32_16x16x32_bf16 v[98:101], v[178:181], v[194:197], v[98:101]
	v_mfma_f32_16x16x32_bf16 v[86:89], v[170:173], v[204:207], v[86:89]
	v_mfma_f32_16x16x32_bf16 v[82:85], v[178:181], v[204:207], v[82:85]
	v_mfma_f32_16x16x32_bf16 v[70:73], v[170:173], v[212:215], v[70:73]
	v_mfma_f32_16x16x32_bf16 v[66:69], v[178:181], v[212:215], v[66:69]
	v_mfma_f32_16x16x32_bf16 v[118:121], v[174:177], v[190:193], v[118:121]
	v_mfma_f32_16x16x32_bf16 v[114:117], v[182:185], v[190:193], v[114:117]
	v_mfma_f32_16x16x32_bf16 v[102:105], v[174:177], v[200:203], v[102:105]
	v_mfma_f32_16x16x32_bf16 v[98:101], v[182:185], v[200:203], v[98:101]
	v_mfma_f32_16x16x32_bf16 v[86:89], v[174:177], v[208:211], v[86:89]
	v_mfma_f32_16x16x32_bf16 v[82:85], v[182:185], v[208:211], v[82:85]
	v_mfma_f32_16x16x32_bf16 v[70:73], v[174:177], v[216:219], v[70:73]
	v_mfma_f32_16x16x32_bf16 v[66:69], v[182:185], v[216:219], v[66:69]
	s_barrier
	s_setprio 0
	s_add_i32 s56, s47, s33
	s_mov_b32 m0, s56
	ds_read_b128 v[186:189], v152 offset:16384
	ds_read_b128 v[190:193], v152 offset:17408
	ds_read_b128 v[194:197], v152 offset:18432
	ds_read_b128 v[200:203], v152 offset:19456
	ds_read_b128 v[204:207], v152 offset:20480
	ds_read_b128 v[208:211], v152 offset:21504
	ds_read_b128 v[212:215], v152 offset:22528
	ds_read_b128 v[216:219], v152 offset:23552
	global_load_lds_dwordx4 v134, s[34:35]
	s_add_i32 m0, s56, 0x2000
	s_add_u32 s56, s34, 0x100000
	s_addc_u32 s57, s35, 0
	s_add_i32 s58, s48, s33
	global_load_lds_dwordx4 v130, s[34:35]
	s_mov_b32 m0, s58
	s_nop 0
	global_load_lds_dwordx4 v134, s[56:57]
	s_add_i32 m0, s58, 0x2000
	s_nop 0
	global_load_lds_dwordx4 v130, s[56:57]
	s_waitcnt vmcnt(6)
	s_waitcnt lgkmcnt(0)
	s_setprio 1
	s_barrier
	v_mfma_f32_16x16x32_bf16 v[62:65], v[154:157], v[186:189], v[62:65]
	v_mfma_f32_16x16x32_bf16 v[58:61], v[162:165], v[186:189], v[58:61]
	v_mfma_f32_16x16x32_bf16 v[46:49], v[154:157], v[194:197], v[46:49]
	v_mfma_f32_16x16x32_bf16 v[42:45], v[162:165], v[194:197], v[42:45]
	v_mfma_f32_16x16x32_bf16 v[30:33], v[154:157], v[204:207], v[30:33]
	v_mfma_f32_16x16x32_bf16 v[26:29], v[162:165], v[204:207], v[26:29]
	v_mfma_f32_16x16x32_bf16 v[14:17], v[154:157], v[212:215], v[14:17]
	v_mfma_f32_16x16x32_bf16 v[10:13], v[162:165], v[212:215], v[10:13]
	v_mfma_f32_16x16x32_bf16 v[62:65], v[158:161], v[190:193], v[62:65]
	v_mfma_f32_16x16x32_bf16 v[58:61], v[166:169], v[190:193], v[58:61]
	v_mfma_f32_16x16x32_bf16 v[46:49], v[158:161], v[200:203], v[46:49]
	v_mfma_f32_16x16x32_bf16 v[42:45], v[166:169], v[200:203], v[42:45]
	v_mfma_f32_16x16x32_bf16 v[30:33], v[158:161], v[208:211], v[30:33]
	v_mfma_f32_16x16x32_bf16 v[26:29], v[166:169], v[208:211], v[26:29]
	v_mfma_f32_16x16x32_bf16 v[14:17], v[158:161], v[216:219], v[14:17]
	v_mfma_f32_16x16x32_bf16 v[10:13], v[166:169], v[216:219], v[10:13]
	v_mfma_f32_16x16x32_bf16 v[54:57], v[170:173], v[186:189], v[54:57]
	v_mfma_f32_16x16x32_bf16 v[50:53], v[178:181], v[186:189], v[50:53]
	v_mfma_f32_16x16x32_bf16 v[38:41], v[170:173], v[194:197], v[38:41]
	v_mfma_f32_16x16x32_bf16 v[34:37], v[178:181], v[194:197], v[34:37]
	v_mfma_f32_16x16x32_bf16 v[22:25], v[170:173], v[204:207], v[22:25]
	v_mfma_f32_16x16x32_bf16 v[18:21], v[178:181], v[204:207], v[18:21]
	v_mfma_f32_16x16x32_bf16 v[6:9], v[170:173], v[212:215], v[6:9]
	v_mfma_f32_16x16x32_bf16 v[2:5], v[178:181], v[212:215], v[2:5]
	v_mfma_f32_16x16x32_bf16 v[54:57], v[174:177], v[190:193], v[54:57]
	v_mfma_f32_16x16x32_bf16 v[50:53], v[182:185], v[190:193], v[50:53]
	v_mfma_f32_16x16x32_bf16 v[38:41], v[174:177], v[200:203], v[38:41]
	v_mfma_f32_16x16x32_bf16 v[34:37], v[182:185], v[200:203], v[34:37]
	v_mfma_f32_16x16x32_bf16 v[22:25], v[174:177], v[208:211], v[22:25]
	v_mfma_f32_16x16x32_bf16 v[18:21], v[182:185], v[208:211], v[18:21]
	v_mfma_f32_16x16x32_bf16 v[6:9], v[174:177], v[216:219], v[6:9]
	v_mfma_f32_16x16x32_bf16 v[2:5], v[182:185], v[216:219], v[2:5]
	s_barrier
; #define PG8_STAGE(bufoff, gbase, voff) do { _Pragma("unroll") for (int _i = 0; _i < 2; ++_i) \
;         __builtin_amdgcn_global_load_lds((const unsigned*)((const char*)(gbase) + (voff)[_i]), (PG8_LAS unsigned*)(lds + (bufoff) + ldsw + _i * 8192), 16, 0, 0); } while (0)
; #define PG8_LDA(dst, b, h) do { _Pragma("unroll") for (int m = 0; m < 4; ++m) _Pragma("unroll") for (int k = 0; k < 2; ++k) dst[m][k] = *(const PG8_LAS bf16x8*)(lds + PG8_SA(b, h) + aoff + m * 2048 + k * 1024); } while (0)
; #define PG8_LDB(dst, b, h) do { _Pragma("unroll") for (int n = 0; n < 2; ++n) _Pragma("unroll") for (int k = 0; k < 2; ++k) dst[n][k] = *(const PG8_LAS bf16x8*)(lds + PG8_SB(b, h) + boff + n * 2048 + k * 1024); } while (0)
; #define PG8_MMA(ai, bj, At, Bt) do { __builtin_amdgcn_s_setprio(1); _Pragma("unroll") for (int m = 0; m < 4; ++m) _Pragma("unroll") for (int n = 0; n < 2; ++n) _Pragma("unroll") for (int k = 0; k < 2; ++k) \
;         acc[ai][bj][m][n] = __builtin_amdgcn_mfma_f32_16x16x32_bf16(Bt[n][k], At[m][k], acc[ai][bj][m][n], 0, 0, 0); __builtin_amdgcn_s_setprio(0); } while (0)
; #define PG8_WAIT_V(n) asm volatile("s_waitcnt vmcnt(" #n ")" ::: "memory")
; #define PG8_WAIT_L(n) asm volatile("s_waitcnt lgkmcnt(" #n ")" ::: "memory")
; #define PG8_BAR __builtin_amdgcn_s_barrier()
; #define PG8_SCHED __builtin_amdgcn_sched_barrier(0)
; template <class Epi, class Sched, bool ALIGN_EPI = false, bool SP2 = false>
; __device__ __forceinline__ void gemm_phase(PG8_LAS unsigned char* lds, const Gemm g, const Sched& S, const Epi& E) {
;     ...
;             PG8_LDB(B0, 1, 0); PG8_LDB(B1, 1, 1); PG8_SCHED; PG8_LDA(At, 1, 0); PG8_STAGE(PG8_SA(0, 1), a2 + hstep, voffA);
;             PG8_WAIT_V(8); PG8_WAIT_L(0); PG8_BAR; PG8_MMA(0, 0, At, B0); PG8_MMA(0, 1, At, B1); PG8_BAR; PG8_SCHED;
;             PG8_LDA(At, 1, 1); PG8_STAGE(PG8_SB(1, 0), b3, voffB); PG8_STAGE(PG8_SB(1, 1), b3 + hstep, voffB); PG8_STAGE(PG8_SA(1, 0), a3, voffA);
;             PG8_WAIT_V(8); PG8_WAIT_L(0); PG8_BAR; PG8_MMA(1, 0, At, B0); PG8_MMA(1, 1, At, B1); PG8_BAR; PG8_SCHED;
;     ...
;         if constexpr (ALIGN_EPI) { if (wr == 0) PG8_BAR; }
	s_setprio 0
	s_mov_b32 m0, s29
	s_nop 0
	global_load_lds_dwordx4 v136, s[36:37]
	s_mov_b32 m0, s40
	s_nop 0
	global_load_lds_dwordx4 v132, s[36:37]
	s_add_i32 s56, 0, 0x18000
	v_add_u32_e32 v153, s56, v148
	s_add_i32 s57, 0, 0x1c000
	ds_read_b128 v[154:157], v153
	ds_read_b128 v[158:161], v153 offset:1024
	ds_read_b128 v[162:165], v153 offset:2048
	ds_read_b128 v[166:169], v153 offset:3072
	v_add_u32_e32 v153, s57, v148
	ds_read_b128 v[170:173], v153
	ds_read_b128 v[174:177], v153 offset:1024
	ds_read_b128 v[178:181], v153 offset:2048
	ds_read_b128 v[182:185], v153 offset:3072
	s_add_u32 s36, s36, 0x100000
	s_addc_u32 s37, s37, 0
	s_mov_b32 m0, s41
	ds_read_b128 v[186:189], v152 offset:32768
	ds_read_b128 v[190:193], v152 offset:33792
	ds_read_b128 v[194:197], v152 offset:34816
	ds_read_b128 v[200:203], v152 offset:35840
	ds_read_b128 v[204:207], v152 offset:36864
	ds_read_b128 v[208:211], v152 offset:37888
	ds_read_b128 v[212:215], v152 offset:38912
	ds_read_b128 v[216:219], v152 offset:39936
	global_load_lds_dwordx4 v136, s[36:37]
	s_mov_b32 m0, s42
	s_nop 0
	global_load_lds_dwordx4 v132, s[36:37]
	s_waitcnt vmcnt(8)
	s_waitcnt lgkmcnt(0)
	s_setprio 1
	s_barrier
	v_mfma_f32_16x16x32_bf16 v[126:129], v[154:157], v[186:189], v[126:129]
	v_mfma_f32_16x16x32_bf16 v[122:125], v[162:165], v[186:189], v[122:125]
	v_mfma_f32_16x16x32_bf16 v[110:113], v[154:157], v[194:197], v[110:113]
	v_mfma_f32_16x16x32_bf16 v[106:109], v[162:165], v[194:197], v[106:109]
	v_mfma_f32_16x16x32_bf16 v[94:97], v[154:157], v[204:207], v[94:97]
	v_mfma_f32_16x16x32_bf16 v[90:93], v[162:165], v[204:207], v[90:93]
	v_mfma_f32_16x16x32_bf16 v[78:81], v[154:157], v[212:215], v[78:81]
	v_mfma_f32_16x16x32_bf16 v[74:77], v[162:165], v[212:215], v[74:77]
	v_mfma_f32_16x16x32_bf16 v[126:129], v[158:161], v[190:193], v[126:129]
	v_mfma_f32_16x16x32_bf16 v[122:125], v[166:169], v[190:193], v[122:125]
	v_mfma_f32_16x16x32_bf16 v[110:113], v[158:161], v[200:203], v[110:113]
	v_mfma_f32_16x16x32_bf16 v[106:109], v[166:169], v[200:203], v[106:109]
	v_mfma_f32_16x16x32_bf16 v[94:97], v[158:161], v[208:211], v[94:97]
	v_mfma_f32_16x16x32_bf16 v[90:93], v[166:169], v[208:211], v[90:93]
	v_mfma_f32_16x16x32_bf16 v[78:81], v[158:161], v[216:219], v[78:81]
	v_mfma_f32_16x16x32_bf16 v[74:77], v[166:169], v[216:219], v[74:77]
	v_mfma_f32_16x16x32_bf16 v[118:121], v[170:173], v[186:189], v[118:121]
	v_mfma_f32_16x16x32_bf16 v[114:117], v[178:181], v[186:189], v[114:117]
	v_mfma_f32_16x16x32_bf16 v[102:105], v[170:173], v[194:197], v[102:105]
	v_mfma_f32_16x16x32_bf16 v[98:101], v[178:181], v[194:197], v[98:101]
	v_mfma_f32_16x16x32_bf16 v[86:89], v[170:173], v[204:207], v[86:89]
	v_mfma_f32_16x16x32_bf16 v[82:85], v[178:181], v[204:207], v[82:85]
	v_mfma_f32_16x16x32_bf16 v[70:73], v[170:173], v[212:215], v[70:73]
	v_mfma_f32_16x16x32_bf16 v[66:69], v[178:181], v[212:215], v[66:69]
	v_mfma_f32_16x16x32_bf16 v[118:121], v[174:177], v[190:193], v[118:121]
	v_mfma_f32_16x16x32_bf16 v[114:117], v[182:185], v[190:193], v[114:117]
	v_mfma_f32_16x16x32_bf16 v[102:105], v[174:177], v[200:203], v[102:105]
	v_mfma_f32_16x16x32_bf16 v[98:101], v[182:185], v[200:203], v[98:101]
	v_mfma_f32_16x16x32_bf16 v[86:89], v[174:177], v[208:211], v[86:89]
	v_mfma_f32_16x16x32_bf16 v[82:85], v[182:185], v[208:211], v[82:85]
	v_mfma_f32_16x16x32_bf16 v[70:73], v[174:177], v[216:219], v[70:73]
	v_mfma_f32_16x16x32_bf16 v[66:69], v[182:185], v[216:219], v[66:69]
	s_barrier
	s_setprio 0
	s_add_i32 s36, s56, s33
	s_add_u32 s34, s34, 0x80
	s_addc_u32 s35, s35, 0
	s_mov_b32 m0, s36
	ds_read_b128 v[186:189], v152 offset:49152
	ds_read_b128 v[190:193], v152 offset:50176
	ds_read_b128 v[194:197], v152 offset:51200
	ds_read_b128 v[200:203], v152 offset:52224
	ds_read_b128 v[204:207], v152 offset:53248
	ds_read_b128 v[208:211], v152 offset:54272
	ds_read_b128 v[212:215], v152 offset:55296
	ds_read_b128 v[216:219], v152 offset:56320
	global_load_lds_dwordx4 v134, s[34:35]
	s_add_i32 m0, s36, 0x2000
	s_add_i32 s36, s57, s33
	global_load_lds_dwordx4 v130, s[34:35]
	s_add_u32 s34, s34, 0x100000
	s_addc_u32 s35, s35, 0
	s_mov_b32 m0, s36
	s_nop 0
	global_load_lds_dwordx4 v134, s[34:35]
	s_add_i32 m0, s36, 0x2000
	s_nop 0
	global_load_lds_dwordx4 v130, s[34:35]
	s_waitcnt vmcnt(6)
	s_waitcnt lgkmcnt(0)
	s_setprio 1
	s_barrier
	v_mfma_f32_16x16x32_bf16 v[62:65], v[154:157], v[186:189], v[62:65]
	v_mfma_f32_16x16x32_bf16 v[58:61], v[162:165], v[186:189], v[58:61]
	v_mfma_f32_16x16x32_bf16 v[46:49], v[154:157], v[194:197], v[46:49]
	v_mfma_f32_16x16x32_bf16 v[42:45], v[162:165], v[194:197], v[42:45]
	v_mfma_f32_16x16x32_bf16 v[30:33], v[154:157], v[204:207], v[30:33]
	v_mfma_f32_16x16x32_bf16 v[26:29], v[162:165], v[204:207], v[26:29]
	v_mfma_f32_16x16x32_bf16 v[14:17], v[154:157], v[212:215], v[14:17]
	v_mfma_f32_16x16x32_bf16 v[10:13], v[162:165], v[212:215], v[10:13]
	v_mfma_f32_16x16x32_bf16 v[62:65], v[158:161], v[190:193], v[62:65]
	v_mfma_f32_16x16x32_bf16 v[58:61], v[166:169], v[190:193], v[58:61]
	v_mfma_f32_16x16x32_bf16 v[46:49], v[158:161], v[200:203], v[46:49]
	v_mfma_f32_16x16x32_bf16 v[42:45], v[166:169], v[200:203], v[42:45]
	v_mfma_f32_16x16x32_bf16 v[30:33], v[158:161], v[208:211], v[30:33]
	v_mfma_f32_16x16x32_bf16 v[26:29], v[166:169], v[208:211], v[26:29]
	v_mfma_f32_16x16x32_bf16 v[14:17], v[158:161], v[216:219], v[14:17]
	v_mfma_f32_16x16x32_bf16 v[10:13], v[166:169], v[216:219], v[10:13]
	v_mfma_f32_16x16x32_bf16 v[54:57], v[170:173], v[186:189], v[54:57]
	v_mfma_f32_16x16x32_bf16 v[50:53], v[178:181], v[186:189], v[50:53]
	v_mfma_f32_16x16x32_bf16 v[38:41], v[170:173], v[194:197], v[38:41]
	v_mfma_f32_16x16x32_bf16 v[34:37], v[178:181], v[194:197], v[34:37]
	v_mfma_f32_16x16x32_bf16 v[22:25], v[170:173], v[204:207], v[22:25]
	v_mfma_f32_16x16x32_bf16 v[18:21], v[178:181], v[204:207], v[18:21]
	v_mfma_f32_16x16x32_bf16 v[6:9], v[170:173], v[212:215], v[6:9]
	v_mfma_f32_16x16x32_bf16 v[2:5], v[178:181], v[212:215], v[2:5]
	v_mfma_f32_16x16x32_bf16 v[54:57], v[174:177], v[190:193], v[54:57]
	v_mfma_f32_16x16x32_bf16 v[50:53], v[182:185], v[190:193], v[50:53]
	v_mfma_f32_16x16x32_bf16 v[38:41], v[174:177], v[200:203], v[38:41]
	v_mfma_f32_16x16x32_bf16 v[34:37], v[182:185], v[200:203], v[34:37]
	v_mfma_f32_16x16x32_bf16 v[22:25], v[174:177], v[208:211], v[22:25]
	v_mfma_f32_16x16x32_bf16 v[18:21], v[182:185], v[208:211], v[18:21]
	v_mfma_f32_16x16x32_bf16 v[6:9], v[174:177], v[216:219], v[6:9]
	v_mfma_f32_16x16x32_bf16 v[2:5], v[182:185], v[216:219], v[2:5]
	s_barrier
	s_setprio 0
	s_add_i32 s55, s55, 2
	s_add_u32 s30, s30, 0x100
	s_addc_u32 s31, s31, 0
	s_add_u32 s53, s53, 0x100
	s_addc_u32 s54, s54, 0
	s_cmp_gt_u32 s55, 61
	s_cbranch_scc0 .LBB0_1081
	s_and_b64 vcc, exec, s[10:11]
	s_cbranch_vccz .LBB0_1084
	s_barrier

; #define PG8_STAGE(bufoff, gbase, voff) do { _Pragma("unroll") for (int _i = 0; _i < 2; ++_i) \
;         __builtin_amdgcn_global_load_lds((const unsigned*)((const char*)(gbase) + (voff)[_i]), (PG8_LAS unsigned*)(lds + (bufoff) + ldsw + _i * 8192), 16, 0, 0); } while (0)
; #define PG8_LDA(dst, b, h) do { _Pragma("unroll") for (int m = 0; m < 4; ++m) _Pragma("unroll") for (int k = 0; k < 2; ++k) dst[m][k] = *(const PG8_LAS bf16x8*)(lds + PG8_SA(b, h) + aoff + m * 2048 + k * 1024); } while (0)
; #define PG8_LDB(dst, b, h) do { _Pragma("unroll") for (int n = 0; n < 2; ++n) _Pragma("unroll") for (int k = 0; k < 2; ++k) dst[n][k] = *(const PG8_LAS bf16x8*)(lds + PG8_SB(b, h) + boff + n * 2048 + k * 1024); } while (0)
; #define PG8_MMA(ai, bj, At, Bt) do { __builtin_amdgcn_s_setprio(1); _Pragma("unroll") for (int m = 0; m < 4; ++m) _Pragma("unroll") for (int n = 0; n < 2; ++n) _Pragma("unroll") for (int k = 0; k < 2; ++k) \
;         acc[ai][bj][m][n] = __builtin_amdgcn_mfma_f32_16x16x32_bf16(Bt[n][k], At[m][k], acc[ai][bj][m][n], 0, 0, 0); __builtin_amdgcn_s_setprio(0); } while (0)
; #define PG8_WAIT_V(n) asm volatile("s_waitcnt vmcnt(" #n ")" ::: "memory")
; #define PG8_BAR __builtin_amdgcn_s_barrier()
; template <class Epi, class Sched, bool ALIGN_EPI = false, bool SP2 = false>
; __device__ __forceinline__ void gemm_phase(PG8_LAS unsigned char* lds, const Gemm g, const Sched& S, const Epi& E) {
;     ...
;         for (int t = 0; t < nt; t += 2) {
;             const bool last = (t == nt - 2);
;             const char* a1 = cA + (size_t)(t + 1) * kstep;
;             const char* a2 = last ? nA : cA + (size_t)(t + 2) * kstep; const char* b2 = last ? nB : cB + (size_t)(t + 2) * kstep;
;             const char* a3 = a2 + kstep; const char* b3 = b2 + kstep;
;             if (last && has_next) S.a_ready(nxt);
;             if constexpr (SP2) {
;             PG8_LDB(B0, 0, 0); PG8_LDB(B1, 0, 1); PG8_SCHED; PG8_LDA(At, 0, 0); PG8_STAGE(PG8_SA(1, 1), a1 + hstep, voffA);
;             PG8_WAIT_V(8); PG8_WAIT_L(0); PG8_BAR; PG8_MMA(0, 0, At, B0); PG8_MMA(0, 1, At, B1); PG8_BAR; PG8_SCHED;
;             PG8_LDA(At, 0, 1); PG8_STAGE(PG8_SB(0, 0), b2, voffB); PG8_STAGE(PG8_SB(0, 1), b2 + hstep, voffB); PG8_STAGE(PG8_SA(0, 0), a2, voffA);
;             PG8_WAIT_V(8); PG8_WAIT_L(0); PG8_BAR; PG8_MMA(1, 0, At, B0); PG8_MMA(1, 1, At, B1); PG8_BAR; PG8_SCHED;
.LBB0_1164:
	s_add_u32 s16, s14, 0xffd50000
	s_addc_u32 s17, s15, -1
	s_mov_b32 m0, s29
	s_nop 0
	global_load_lds_dwordx4 v128, s[16:17]
	s_mov_b32 m0, s30
	s_nop 0
	global_load_lds_dwordx4 v130, s[16:17]
	s_add_u32 s16, s16, 0x80
	s_addc_u32 s17, s17, 0
	ds_read_b128 v[140:143], v193
	ds_read_b128 v[144:147], v193 offset:1024
	ds_read_b128 v[148:151], v193 offset:2048
	ds_read_b128 v[152:155], v193 offset:3072
	ds_read_b128 v[156:159], v194
	ds_read_b128 v[160:163], v194 offset:1024
	ds_read_b128 v[164:167], v194 offset:2048
	ds_read_b128 v[168:171], v194 offset:3072
	s_cmpk_eq_i32 s41, 0xa8
	s_cselect_b32 s21, s5, s17
	s_cselect_b32 s20, s4, s16
	s_cselect_b32 s17, s13, s40
	s_cselect_b32 s16, s12, s39
	s_add_i32 m0, s24, 0xc000
	ds_read_b128 v[172:175], v195
	ds_read_b128 v[176:179], v195 offset:1024
	ds_read_b128 v[180:183], v195 offset:2048
	ds_read_b128 v[184:187], v195 offset:3072
	ds_read_b128 v[196:199], v195 offset:4096
	ds_read_b128 v[200:203], v195 offset:5120
	ds_read_b128 v[204:207], v195 offset:6144
	ds_read_b128 v[208:211], v195 offset:7168
	global_load_lds_dwordx4 v132, s[14:15]
	s_add_i32 m0, s24, 0xe000
	s_nop 0
	global_load_lds_dwordx4 v134, s[14:15]
	s_waitcnt vmcnt(8)
	s_waitcnt lgkmcnt(0)
	s_setprio 1
	s_barrier
	v_mfma_f32_16x16x32_bf16 v[124:127], v[140:143], v[172:175], v[124:127]
	v_mfma_f32_16x16x32_bf16 v[120:123], v[148:151], v[172:175], v[120:123]
	v_mfma_f32_16x16x32_bf16 v[112:115], v[140:143], v[180:183], v[112:115]
	v_mfma_f32_16x16x32_bf16 v[104:107], v[148:151], v[180:183], v[104:107]
	v_mfma_f32_16x16x32_bf16 v[96:99], v[140:143], v[196:199], v[96:99]
	v_mfma_f32_16x16x32_bf16 v[88:91], v[148:151], v[196:199], v[88:91]
	v_mfma_f32_16x16x32_bf16 v[80:83], v[140:143], v[204:207], v[80:83]
	v_mfma_f32_16x16x32_bf16 v[72:75], v[148:151], v[204:207], v[72:75]
	v_mfma_f32_16x16x32_bf16 v[124:127], v[144:147], v[176:179], v[124:127]
	v_mfma_f32_16x16x32_bf16 v[120:123], v[152:155], v[176:179], v[120:123]
	v_mfma_f32_16x16x32_bf16 v[112:115], v[144:147], v[184:187], v[112:115]
	v_mfma_f32_16x16x32_bf16 v[104:107], v[152:155], v[184:187], v[104:107]
	v_mfma_f32_16x16x32_bf16 v[96:99], v[144:147], v[200:203], v[96:99]
	v_mfma_f32_16x16x32_bf16 v[88:91], v[152:155], v[200:203], v[88:91]
	v_mfma_f32_16x16x32_bf16 v[80:83], v[144:147], v[208:211], v[80:83]
	v_mfma_f32_16x16x32_bf16 v[72:75], v[152:155], v[208:211], v[72:75]
	v_mfma_f32_16x16x32_bf16 v[116:119], v[156:159], v[172:175], v[116:119]
	v_mfma_f32_16x16x32_bf16 v[108:111], v[164:167], v[172:175], v[108:111]
	v_mfma_f32_16x16x32_bf16 v[100:103], v[156:159], v[180:183], v[100:103]
	v_mfma_f32_16x16x32_bf16 v[92:95], v[164:167], v[180:183], v[92:95]
	v_mfma_f32_16x16x32_bf16 v[84:87], v[156:159], v[196:199], v[84:87]
	v_mfma_f32_16x16x32_bf16 v[76:79], v[164:167], v[196:199], v[76:79]
	v_mfma_f32_16x16x32_bf16 v[68:71], v[156:159], v[204:207], v[68:71]
	v_mfma_f32_16x16x32_bf16 v[64:67], v[164:167], v[204:207], v[64:67]
	v_mfma_f32_16x16x32_bf16 v[116:119], v[160:163], v[176:179], v[116:119]
	v_mfma_f32_16x16x32_bf16 v[108:111], v[168:171], v[176:179], v[108:111]
	v_mfma_f32_16x16x32_bf16 v[100:103], v[160:163], v[184:187], v[100:103]
	v_mfma_f32_16x16x32_bf16 v[92:95], v[168:171], v[184:187], v[92:95]
	v_mfma_f32_16x16x32_bf16 v[84:87], v[160:163], v[200:203], v[84:87]
	v_mfma_f32_16x16x32_bf16 v[76:79], v[168:171], v[200:203], v[76:79]
	v_mfma_f32_16x16x32_bf16 v[68:71], v[160:163], v[208:211], v[68:71]
	v_mfma_f32_16x16x32_bf16 v[64:67], v[168:171], v[208:211], v[64:67]
	s_barrier
	s_setprio 0
	s_add_i32 s42, s33, s23
	s_mov_b32 m0, s42
	ds_read_b128 v[172:175], v195 offset:16384
	ds_read_b128 v[176:179], v195 offset:17408
	ds_read_b128 v[180:183], v195 offset:18432
	ds_read_b128 v[184:187], v195 offset:19456
	ds_read_b128 v[196:199], v195 offset:20480
	ds_read_b128 v[200:203], v195 offset:21504
	ds_read_b128 v[204:207], v195 offset:22528
	ds_read_b128 v[208:211], v195 offset:23552
	global_load_lds_dwordx4 v128, s[16:17]
	s_add_i32 m0, s42, 0x2000
	s_add_u32 s42, s16, 0x2b0000
	s_addc_u32 s43, s17, 0
	s_add_i32 s44, s34, s23
	global_load_lds_dwordx4 v130, s[16:17]
	s_mov_b32 m0, s44
	s_nop 0
	global_load_lds_dwordx4 v128, s[42:43]
	s_add_i32 m0, s44, 0x2000
	s_nop 0
	global_load_lds_dwordx4 v130, s[42:43]
	s_waitcnt vmcnt(6)
	s_waitcnt lgkmcnt(0)
	s_setprio 1
	s_barrier
	v_mfma_f32_16x16x32_bf16 v[60:63], v[140:143], v[172:175], v[60:63]
	v_mfma_f32_16x16x32_bf16 v[56:59], v[148:151], v[172:175], v[56:59]
	v_mfma_f32_16x16x32_bf16 v[48:51], v[140:143], v[180:183], v[48:51]
	v_mfma_f32_16x16x32_bf16 v[40:43], v[148:151], v[180:183], v[40:43]
	v_mfma_f32_16x16x32_bf16 v[32:35], v[140:143], v[196:199], v[32:35]
	v_mfma_f32_16x16x32_bf16 v[24:27], v[148:151], v[196:199], v[24:27]
	v_mfma_f32_16x16x32_bf16 v[16:19], v[140:143], v[204:207], v[16:19]
	v_mfma_f32_16x16x32_bf16 v[8:11], v[148:151], v[204:207], v[8:11]
	v_mfma_f32_16x16x32_bf16 v[60:63], v[144:147], v[176:179], v[60:63]
	v_mfma_f32_16x16x32_bf16 v[56:59], v[152:155], v[176:179], v[56:59]
	v_mfma_f32_16x16x32_bf16 v[48:51], v[144:147], v[184:187], v[48:51]
	v_mfma_f32_16x16x32_bf16 v[40:43], v[152:155], v[184:187], v[40:43]
	v_mfma_f32_16x16x32_bf16 v[32:35], v[144:147], v[200:203], v[32:35]
	v_mfma_f32_16x16x32_bf16 v[24:27], v[152:155], v[200:203], v[24:27]
	v_mfma_f32_16x16x32_bf16 v[16:19], v[144:147], v[208:211], v[16:19]
	v_mfma_f32_16x16x32_bf16 v[8:11], v[152:155], v[208:211], v[8:11]
	v_mfma_f32_16x16x32_bf16 v[52:55], v[156:159], v[172:175], v[52:55]
	v_mfma_f32_16x16x32_bf16 v[44:47], v[164:167], v[172:175], v[44:47]
	v_mfma_f32_16x16x32_bf16 v[36:39], v[156:159], v[180:183], v[36:39]
	v_mfma_f32_16x16x32_bf16 v[28:31], v[164:167], v[180:183], v[28:31]
	v_mfma_f32_16x16x32_bf16 v[20:23], v[156:159], v[196:199], v[20:23]
	v_mfma_f32_16x16x32_bf16 v[12:15], v[164:167], v[196:199], v[12:15]
	v_mfma_f32_16x16x32_bf16 v[4:7], v[156:159], v[204:207], v[4:7]
	v_mfma_f32_16x16x32_bf16 v[0:3], v[164:167], v[204:207], v[0:3]
	v_mfma_f32_16x16x32_bf16 v[52:55], v[160:163], v[176:179], v[52:55]
	v_mfma_f32_16x16x32_bf16 v[44:47], v[168:171], v[176:179], v[44:47]
	v_mfma_f32_16x16x32_bf16 v[36:39], v[160:163], v[184:187], v[36:39]
	v_mfma_f32_16x16x32_bf16 v[28:31], v[168:171], v[184:187], v[28:31]
	v_mfma_f32_16x16x32_bf16 v[20:23], v[160:163], v[200:203], v[20:23]
	v_mfma_f32_16x16x32_bf16 v[12:15], v[168:171], v[200:203], v[12:15]
	v_mfma_f32_16x16x32_bf16 v[4:7], v[160:163], v[208:211], v[4:7]
	v_mfma_f32_16x16x32_bf16 v[0:3], v[168:171], v[208:211], v[0:3]
	s_barrier
; #define PG8_STAGE(bufoff, gbase, voff) do { _Pragma("unroll") for (int _i = 0; _i < 2; ++_i) \
;         __builtin_amdgcn_global_load_lds((const unsigned*)((const char*)(gbase) + (voff)[_i]), (PG8_LAS unsigned*)(lds + (bufoff) + ldsw + _i * 8192), 16, 0, 0); } while (0)
; #define PG8_LDA(dst, b, h) do { _Pragma("unroll") for (int m = 0; m < 4; ++m) _Pragma("unroll") for (int k = 0; k < 2; ++k) dst[m][k] = *(const PG8_LAS bf16x8*)(lds + PG8_SA(b, h) + aoff + m * 2048 + k * 1024); } while (0)
; #define PG8_LDB(dst, b, h) do { _Pragma("unroll") for (int n = 0; n < 2; ++n) _Pragma("unroll") for (int k = 0; k < 2; ++k) dst[n][k] = *(const PG8_LAS bf16x8*)(lds + PG8_SB(b, h) + boff + n * 2048 + k * 1024); } while (0)
; #define PG8_MMA(ai, bj, At, Bt) do { __builtin_amdgcn_s_setprio(1); _Pragma("unroll") for (int m = 0; m < 4; ++m) _Pragma("unroll") for (int n = 0; n < 2; ++n) _Pragma("unroll") for (int k = 0; k < 2; ++k) \
;         acc[ai][bj][m][n] = __builtin_amdgcn_mfma_f32_16x16x32_bf16(Bt[n][k], At[m][k], acc[ai][bj][m][n], 0, 0, 0); __builtin_amdgcn_s_setprio(0); } while (0)
; #define PG8_WAIT_V(n) asm volatile("s_waitcnt vmcnt(" #n ")" ::: "memory")
; #define PG8_WAIT_L(n) asm volatile("s_waitcnt lgkmcnt(" #n ")" ::: "memory")
; #define PG8_BAR __builtin_amdgcn_s_barrier()
; #define PG8_SCHED __builtin_amdgcn_sched_barrier(0)
; template <class Epi, class Sched, bool ALIGN_EPI = false, bool SP2 = false>
; __device__ __forceinline__ void gemm_phase(PG8_LAS unsigned char* lds, const Gemm g, const Sched& S, const Epi& E) {
;     ...
;             PG8_LDB(B0, 1, 0); PG8_LDB(B1, 1, 1); PG8_SCHED; PG8_LDA(At, 1, 0); PG8_STAGE(PG8_SA(0, 1), a2 + hstep, voffA);
;             PG8_WAIT_V(8); PG8_WAIT_L(0); PG8_BAR; PG8_MMA(0, 0, At, B0); PG8_MMA(0, 1, At, B1); PG8_BAR; PG8_SCHED;
;             PG8_LDA(At, 1, 1); PG8_STAGE(PG8_SB(1, 0), b3, voffB); PG8_STAGE(PG8_SB(1, 1), b3 + hstep, voffB); PG8_STAGE(PG8_SA(1, 0), a3, voffA);
;             PG8_WAIT_V(8); PG8_WAIT_L(0); PG8_BAR; PG8_MMA(1, 0, At, B0); PG8_MMA(1, 1, At, B1); PG8_BAR; PG8_SCHED;
;     ...
;         if constexpr (ALIGN_EPI) { if (wr == 0) PG8_BAR; }
	s_setprio 0
	s_mov_b32 m0, s24
	s_nop 0
	global_load_lds_dwordx4 v128, s[20:21]
	s_mov_b32 m0, s25
	s_nop 0
	global_load_lds_dwordx4 v130, s[20:21]
	s_add_i32 s42, 0, 0x18000
	s_add_i32 s43, 0, 0x1c000
	v_add_u32_e32 v152, s42, v191
	v_add_u32_e32 v168, s43, v191
	ds_read_b128 v[140:143], v152
	ds_read_b128 v[144:147], v152 offset:1024
	ds_read_b128 v[148:151], v152 offset:2048
	ds_read_b128 v[152:155], v152 offset:3072
	ds_read_b128 v[156:159], v168
	ds_read_b128 v[160:163], v168 offset:1024
	ds_read_b128 v[164:167], v168 offset:2048
	ds_read_b128 v[168:171], v168 offset:3072
	s_add_u32 s20, s20, 0x2b0000
	s_addc_u32 s21, s21, 0
	s_mov_b32 m0, s26
	ds_read_b128 v[172:175], v195 offset:32768
	ds_read_b128 v[176:179], v195 offset:33792
	ds_read_b128 v[180:183], v195 offset:34816
	ds_read_b128 v[184:187], v195 offset:35840
	ds_read_b128 v[196:199], v195 offset:36864
	ds_read_b128 v[200:203], v195 offset:37888
	ds_read_b128 v[204:207], v195 offset:38912
	ds_read_b128 v[208:211], v195 offset:39936
	global_load_lds_dwordx4 v128, s[20:21]
	s_mov_b32 m0, s27
	s_nop 0
	global_load_lds_dwordx4 v130, s[20:21]
	s_waitcnt vmcnt(8)
	s_waitcnt lgkmcnt(0)
	s_setprio 1
	s_barrier
	v_mfma_f32_16x16x32_bf16 v[124:127], v[140:143], v[172:175], v[124:127]
	v_mfma_f32_16x16x32_bf16 v[120:123], v[148:151], v[172:175], v[120:123]
	v_mfma_f32_16x16x32_bf16 v[112:115], v[140:143], v[180:183], v[112:115]
	v_mfma_f32_16x16x32_bf16 v[104:107], v[148:151], v[180:183], v[104:107]
	v_mfma_f32_16x16x32_bf16 v[96:99], v[140:143], v[196:199], v[96:99]
	v_mfma_f32_16x16x32_bf16 v[88:91], v[148:151], v[196:199], v[88:91]
	v_mfma_f32_16x16x32_bf16 v[80:83], v[140:143], v[204:207], v[80:83]
	v_mfma_f32_16x16x32_bf16 v[72:75], v[148:151], v[204:207], v[72:75]
	v_mfma_f32_16x16x32_bf16 v[124:127], v[144:147], v[176:179], v[124:127]
	v_mfma_f32_16x16x32_bf16 v[120:123], v[152:155], v[176:179], v[120:123]
	v_mfma_f32_16x16x32_bf16 v[112:115], v[144:147], v[184:187], v[112:115]
	v_mfma_f32_16x16x32_bf16 v[104:107], v[152:155], v[184:187], v[104:107]
	v_mfma_f32_16x16x32_bf16 v[96:99], v[144:147], v[200:203], v[96:99]
	v_mfma_f32_16x16x32_bf16 v[88:91], v[152:155], v[200:203], v[88:91]
	v_mfma_f32_16x16x32_bf16 v[80:83], v[144:147], v[208:211], v[80:83]
	v_mfma_f32_16x16x32_bf16 v[72:75], v[152:155], v[208:211], v[72:75]
	v_mfma_f32_16x16x32_bf16 v[116:119], v[156:159], v[172:175], v[116:119]
	v_mfma_f32_16x16x32_bf16 v[108:111], v[164:167], v[172:175], v[108:111]
	v_mfma_f32_16x16x32_bf16 v[100:103], v[156:159], v[180:183], v[100:103]
	v_mfma_f32_16x16x32_bf16 v[92:95], v[164:167], v[180:183], v[92:95]
	v_mfma_f32_16x16x32_bf16 v[84:87], v[156:159], v[196:199], v[84:87]
	v_mfma_f32_16x16x32_bf16 v[76:79], v[164:167], v[196:199], v[76:79]
	v_mfma_f32_16x16x32_bf16 v[68:71], v[156:159], v[204:207], v[68:71]
	v_mfma_f32_16x16x32_bf16 v[64:67], v[164:167], v[204:207], v[64:67]
	v_mfma_f32_16x16x32_bf16 v[116:119], v[160:163], v[176:179], v[116:119]
	v_mfma_f32_16x16x32_bf16 v[108:111], v[168:171], v[176:179], v[108:111]
	v_mfma_f32_16x16x32_bf16 v[100:103], v[160:163], v[184:187], v[100:103]
	v_mfma_f32_16x16x32_bf16 v[92:95], v[168:171], v[184:187], v[92:95]
	v_mfma_f32_16x16x32_bf16 v[84:87], v[160:163], v[200:203], v[84:87]
	v_mfma_f32_16x16x32_bf16 v[76:79], v[168:171], v[200:203], v[76:79]
	v_mfma_f32_16x16x32_bf16 v[68:71], v[160:163], v[208:211], v[68:71]
	v_mfma_f32_16x16x32_bf16 v[64:67], v[168:171], v[208:211], v[64:67]
	s_barrier
	s_setprio 0
	s_add_i32 s20, s42, s23
	s_add_u32 s16, s16, 0x80
	s_addc_u32 s17, s17, 0
	s_mov_b32 m0, s20
	ds_read_b128 v[172:175], v195 offset:49152
	ds_read_b128 v[176:179], v195 offset:50176
	ds_read_b128 v[180:183], v195 offset:51200
	ds_read_b128 v[184:187], v195 offset:52224
	ds_read_b128 v[196:199], v195 offset:53248
	ds_read_b128 v[200:203], v195 offset:54272
	ds_read_b128 v[204:207], v195 offset:55296
	ds_read_b128 v[208:211], v195 offset:56320
	global_load_lds_dwordx4 v128, s[16:17]
	s_add_i32 m0, s20, 0x2000
	s_add_i32 s20, s43, s23
	global_load_lds_dwordx4 v130, s[16:17]
	s_add_u32 s16, s16, 0x2b0000
	s_addc_u32 s17, s17, 0
	s_mov_b32 m0, s20
	s_nop 0
	global_load_lds_dwordx4 v128, s[16:17]
	s_add_i32 m0, s20, 0x2000
	s_nop 0
	global_load_lds_dwordx4 v130, s[16:17]
	s_waitcnt vmcnt(6)
	s_waitcnt lgkmcnt(0)
	s_setprio 1
	s_barrier
	v_mfma_f32_16x16x32_bf16 v[60:63], v[140:143], v[172:175], v[60:63]
	v_mfma_f32_16x16x32_bf16 v[56:59], v[148:151], v[172:175], v[56:59]
	v_mfma_f32_16x16x32_bf16 v[48:51], v[140:143], v[180:183], v[48:51]
	v_mfma_f32_16x16x32_bf16 v[40:43], v[148:151], v[180:183], v[40:43]
	v_mfma_f32_16x16x32_bf16 v[32:35], v[140:143], v[196:199], v[32:35]
	v_mfma_f32_16x16x32_bf16 v[24:27], v[148:151], v[196:199], v[24:27]
	v_mfma_f32_16x16x32_bf16 v[16:19], v[140:143], v[204:207], v[16:19]
	v_mfma_f32_16x16x32_bf16 v[8:11], v[148:151], v[204:207], v[8:11]
	v_mfma_f32_16x16x32_bf16 v[60:63], v[144:147], v[176:179], v[60:63]
	v_mfma_f32_16x16x32_bf16 v[56:59], v[152:155], v[176:179], v[56:59]
	v_mfma_f32_16x16x32_bf16 v[48:51], v[144:147], v[184:187], v[48:51]
	v_mfma_f32_16x16x32_bf16 v[40:43], v[152:155], v[184:187], v[40:43]
	v_mfma_f32_16x16x32_bf16 v[32:35], v[144:147], v[200:203], v[32:35]
	v_mfma_f32_16x16x32_bf16 v[24:27], v[152:155], v[200:203], v[24:27]
	v_mfma_f32_16x16x32_bf16 v[16:19], v[144:147], v[208:211], v[16:19]
	v_mfma_f32_16x16x32_bf16 v[8:11], v[152:155], v[208:211], v[8:11]
	v_mfma_f32_16x16x32_bf16 v[52:55], v[156:159], v[172:175], v[52:55]
	v_mfma_f32_16x16x32_bf16 v[44:47], v[164:167], v[172:175], v[44:47]
	v_mfma_f32_16x16x32_bf16 v[36:39], v[156:159], v[180:183], v[36:39]
	v_mfma_f32_16x16x32_bf16 v[28:31], v[164:167], v[180:183], v[28:31]
	v_mfma_f32_16x16x32_bf16 v[20:23], v[156:159], v[196:199], v[20:23]
	v_mfma_f32_16x16x32_bf16 v[12:15], v[164:167], v[196:199], v[12:15]
	v_mfma_f32_16x16x32_bf16 v[4:7], v[156:159], v[204:207], v[4:7]
	v_mfma_f32_16x16x32_bf16 v[0:3], v[164:167], v[204:207], v[0:3]
	v_mfma_f32_16x16x32_bf16 v[52:55], v[160:163], v[176:179], v[52:55]
	v_mfma_f32_16x16x32_bf16 v[44:47], v[168:171], v[176:179], v[44:47]
	v_mfma_f32_16x16x32_bf16 v[36:39], v[160:163], v[184:187], v[36:39]
	v_mfma_f32_16x16x32_bf16 v[28:31], v[168:171], v[184:187], v[28:31]
	v_mfma_f32_16x16x32_bf16 v[20:23], v[160:163], v[200:203], v[20:23]
	v_mfma_f32_16x16x32_bf16 v[12:15], v[168:171], v[200:203], v[12:15]
	v_mfma_f32_16x16x32_bf16 v[4:7], v[160:163], v[208:211], v[4:7]
	v_mfma_f32_16x16x32_bf16 v[0:3], v[168:171], v[208:211], v[0:3]
	s_barrier
	s_setprio 0
	s_add_i32 s41, s41, 2
	s_add_u32 s14, s14, 0x100
	s_addc_u32 s15, s15, 0
	s_add_u32 s39, s39, 0x100
	s_addc_u32 s40, s40, 0
	s_cmpk_gt_u32 s41, 0xa9
	s_cbranch_scc0 .LBB0_1164
	s_and_b64 vcc, exec, s[10:11]
	s_cbranch_vccz .LBB0_1167
	s_barrier
